# hand-written k-loops: LDS ring-index update and next-slice read addresses moved from behind the mid-loop barrier into the preceding MFMA shadow (segment head starts with MFMAs)
# speedup vs baseline: 1.0056x; 1.0054x over previous
; template <int MI, int NI>
; DI void gemm256(f32x4 (&acc)[MI][NI], const u16* __restrict__ A, int lda, const u16* __restrict__ Bt, int ldb, int K, int m0, int n0, char* smem) {
;     ...
;   for (int kt = 0; kt < nk; ++kt) {
;     if (kt + 1 < nk) asm volatile("s_waitcnt vmcnt(%0) lgkmcnt(0)" :: "n"(LPS) : "memory");
;     else asm volatile("s_waitcnt vmcnt(0) lgkmcnt(0)" ::: "memory");
;     __builtin_amdgcn_s_barrier();
;     __builtin_amdgcn_s_setprio(1);
;     const char* sb = smem + st * STAGE + foff;
;     bf16x8 af[MI], bfr[NI];
; #pragma unroll
;     for (int mi = 0; mi < MI; ++mi) af[mi] = *(const bf16x8*)(sb + (wr * MI + mi) * 1024);
; #pragma unroll
;     for (int ni = 0; ni < NI; ++ni) bfr[ni] = *(const bf16x8*)(sb + ABYTES + (wc * NI + ni) * 1024);
;     __builtin_amdgcn_sched_barrier(0x0);
;     if (kt + 2 < nk) { const int s2 = st >= 1 ? st - 1 : 2; G256_ISSUE(s2, (kt + 2) * 32); }
;     __builtin_amdgcn_s_setprio(0);
; #pragma unroll
;     for (int mi = 0; mi < MI; ++mi)
; #pragma unroll
;       for (int ni = 0; ni < NI; ++ni)
;         acc[mi][ni] = __builtin_amdgcn_mfma_f32_16x16x32_bf16(bfr[ni], af[mi], acc[mi][ni], 0, 0, 0);
;     st = st == 2 ? 0 : st + 1;
;   }
.Lpipe_mlp1:
	v_add_u32_e32 v160, s11, v143
	ds_read_b128 v[164:167], v160 offset:4096
	ds_read_b128 v[168:171], v160 offset:5120
	ds_read_b128 v[172:175], v160 offset:6144
	ds_read_b128 v[176:179], v160 offset:7168
	s_add_i32 s12, s11, 0xffffa000
	s_cmp_eq_u32 s11, 0
	s_cselect_b32 s12, 0xc000, s12
	s_add_i32 s13, s12, s14
	s_add_i32 s12, s12, s4
	s_mov_b32 m0, s13
	s_waitcnt lgkmcnt(7)
	v_mfma_f32_16x16x32_bf16 v[126:129], v[180:183], v[144:147], v[126:129]
	global_load_lds_dwordx4 v[198:199], off
	v_mfma_f32_16x16x32_bf16 v[110:113], v[180:183], v[148:151], v[110:113]
	v_lshl_add_u64 v[198:199], v[198:199], 0, s[98:99]
	s_add_i32 m0, s13, 0x400
	v_mfma_f32_16x16x32_bf16 v[94:97], v[180:183], v[152:155], v[94:97]
	global_load_lds_dwordx4 v[200:201], off
	v_mfma_f32_16x16x32_bf16 v[78:81], v[180:183], v[156:159], v[78:81]
	v_lshl_add_u64 v[200:201], v[200:201], 0, s[98:99]
	s_add_i32 m0, s13, 0x800
	s_waitcnt lgkmcnt(6)
	v_mfma_f32_16x16x32_bf16 v[122:125], v[184:187], v[144:147], v[122:125]
	global_load_lds_dwordx4 v[202:203], off
	v_mfma_f32_16x16x32_bf16 v[106:109], v[184:187], v[148:151], v[106:109]
	v_lshl_add_u64 v[202:203], v[202:203], 0, s[98:99]
	s_add_i32 m0, s13, 0xc00
	v_mfma_f32_16x16x32_bf16 v[90:93], v[184:187], v[152:155], v[90:93]
	global_load_lds_dwordx4 v[204:205], off
	v_mfma_f32_16x16x32_bf16 v[74:77], v[184:187], v[156:159], v[74:77]
	v_lshl_add_u64 v[204:205], v[204:205], 0, s[98:99]
	s_mov_b32 m0, s12
	s_waitcnt lgkmcnt(5)
	v_mfma_f32_16x16x32_bf16 v[118:121], v[188:191], v[144:147], v[118:121]
	global_load_lds_dwordx4 v[206:207], off
	v_mfma_f32_16x16x32_bf16 v[102:105], v[188:191], v[148:151], v[102:105]
	v_lshl_add_u64 v[206:207], v[206:207], 0, s[98:99]
	s_add_i32 m0, s12, 0x400
	v_mfma_f32_16x16x32_bf16 v[86:89], v[188:191], v[152:155], v[86:89]
	global_load_lds_dwordx4 v[208:209], off
	v_mfma_f32_16x16x32_bf16 v[70:73], v[188:191], v[156:159], v[70:73]
	v_lshl_add_u64 v[208:209], v[208:209], 0, s[98:99]
	s_waitcnt lgkmcnt(4)
	v_mfma_f32_16x16x32_bf16 v[114:117], v[192:195], v[144:147], v[114:117]
	s_add_i32 s13, s11, 0x6000
	v_mfma_f32_16x16x32_bf16 v[98:101], v[192:195], v[148:151], v[98:101]
	s_cmp_eq_u32 s11, 0xc000
	s_cselect_b32 s11, 0, s13
	v_mfma_f32_16x16x32_bf16 v[82:85], v[192:195], v[152:155], v[82:85]
	v_add_u32_e32 v196, s11, v143
	v_mfma_f32_16x16x32_bf16 v[66:69], v[192:195], v[156:159], v[66:69]
	v_add_u32_e32 v197, s11, v0
	s_waitcnt vmcnt(6) lgkmcnt(0)
	s_barrier
	v_mfma_f32_16x16x32_bf16 v[62:65], v[180:183], v[164:167], v[62:65]
	ds_read_b128 v[144:147], v196
	v_mfma_f32_16x16x32_bf16 v[46:49], v[180:183], v[168:171], v[46:49]
	ds_read_b128 v[148:151], v196 offset:1024
	v_mfma_f32_16x16x32_bf16 v[30:33], v[180:183], v[172:175], v[30:33]
	ds_read_b128 v[152:155], v196 offset:2048
	v_mfma_f32_16x16x32_bf16 v[14:17], v[180:183], v[176:179], v[14:17]
	ds_read_b128 v[156:159], v196 offset:3072
	ds_read_b128 v[180:183], v197 offset:16384
	v_mfma_f32_16x16x32_bf16 v[58:61], v[184:187], v[164:167], v[58:61]
	v_mfma_f32_16x16x32_bf16 v[42:45], v[184:187], v[168:171], v[42:45]
	v_mfma_f32_16x16x32_bf16 v[26:29], v[184:187], v[172:175], v[26:29]
	v_mfma_f32_16x16x32_bf16 v[10:13], v[184:187], v[176:179], v[10:13]
	ds_read_b128 v[184:187], v197 offset:17408
	v_mfma_f32_16x16x32_bf16 v[54:57], v[188:191], v[164:167], v[54:57]
	v_mfma_f32_16x16x32_bf16 v[38:41], v[188:191], v[168:171], v[38:41]
	v_mfma_f32_16x16x32_bf16 v[22:25], v[188:191], v[172:175], v[22:25]
	v_mfma_f32_16x16x32_bf16 v[6:9], v[188:191], v[176:179], v[6:9]
	ds_read_b128 v[188:191], v197 offset:18432
	v_mfma_f32_16x16x32_bf16 v[50:53], v[192:195], v[164:167], v[50:53]
	v_mfma_f32_16x16x32_bf16 v[34:37], v[192:195], v[168:171], v[34:37]
	v_mfma_f32_16x16x32_bf16 v[18:21], v[192:195], v[172:175], v[18:21]
	v_mfma_f32_16x16x32_bf16 v[2:5], v[192:195], v[176:179], v[2:5]
	ds_read_b128 v[192:195], v197 offset:19456
	s_sub_i32 s5, s5, 1
	s_cmp_lg_u32 s5, 0
	s_cbranch_scc1 .Lpipe_mlp1
	v_add_u32_e32 v160, s11, v143
	ds_read_b128 v[164:167], v160 offset:4096
	ds_read_b128 v[168:171], v160 offset:5120
	ds_read_b128 v[172:175], v160 offset:6144
	ds_read_b128 v[176:179], v160 offset:7168
	s_add_i32 s12, s11, 0xffffa000
	s_cmp_eq_u32 s11, 0
	s_cselect_b32 s12, 0xc000, s12
	s_add_i32 s13, s12, s14
	s_add_i32 s12, s12, s4
	s_mov_b32 m0, s13
	s_waitcnt lgkmcnt(7)
	v_mfma_f32_16x16x32_bf16 v[126:129], v[180:183], v[144:147], v[126:129]
	global_load_lds_dwordx4 v[198:199], off
	v_mfma_f32_16x16x32_bf16 v[110:113], v[180:183], v[148:151], v[110:113]
	v_lshl_add_u64 v[198:199], v[198:199], 0, s[98:99]
	s_add_i32 m0, s13, 0x400
	v_mfma_f32_16x16x32_bf16 v[94:97], v[180:183], v[152:155], v[94:97]
	global_load_lds_dwordx4 v[200:201], off
	v_mfma_f32_16x16x32_bf16 v[78:81], v[180:183], v[156:159], v[78:81]
	v_lshl_add_u64 v[200:201], v[200:201], 0, s[98:99]
	s_add_i32 m0, s13, 0x800
	s_waitcnt lgkmcnt(6)
	v_mfma_f32_16x16x32_bf16 v[122:125], v[184:187], v[144:147], v[122:125]
	global_load_lds_dwordx4 v[202:203], off
	v_mfma_f32_16x16x32_bf16 v[106:109], v[184:187], v[148:151], v[106:109]
	v_lshl_add_u64 v[202:203], v[202:203], 0, s[98:99]
	s_add_i32 m0, s13, 0xc00
	v_mfma_f32_16x16x32_bf16 v[90:93], v[184:187], v[152:155], v[90:93]
	global_load_lds_dwordx4 v[204:205], off
	v_mfma_f32_16x16x32_bf16 v[74:77], v[184:187], v[156:159], v[74:77]
	v_lshl_add_u64 v[204:205], v[204:205], 0, s[98:99]
	s_mov_b32 m0, s12
	s_waitcnt lgkmcnt(5)
; template <int MI, int NI>
; DI void gemm256(f32x4 (&acc)[MI][NI], const u16* __restrict__ A, int lda, const u16* __restrict__ Bt, int ldb, int K, int m0, int n0, char* smem) {
;     ...
;   for (int kt = 0; kt < nk; ++kt) {
;     if (kt + 1 < nk) asm volatile("s_waitcnt vmcnt(%0) lgkmcnt(0)" :: "n"(LPS) : "memory");
;     else asm volatile("s_waitcnt vmcnt(0) lgkmcnt(0)" ::: "memory");
;     __builtin_amdgcn_s_barrier();
;     __builtin_amdgcn_s_setprio(1);
;     const char* sb = smem + st * STAGE + foff;
;     bf16x8 af[MI], bfr[NI];
; #pragma unroll
;     for (int mi = 0; mi < MI; ++mi) af[mi] = *(const bf16x8*)(sb + (wr * MI + mi) * 1024);
; #pragma unroll
;     for (int ni = 0; ni < NI; ++ni) bfr[ni] = *(const bf16x8*)(sb + ABYTES + (wc * NI + ni) * 1024);
;     __builtin_amdgcn_sched_barrier(0x0);
;     if (kt + 2 < nk) { const int s2 = st >= 1 ? st - 1 : 2; G256_ISSUE(s2, (kt + 2) * 32); }
;     __builtin_amdgcn_s_setprio(0);
; #pragma unroll
;     for (int mi = 0; mi < MI; ++mi)
; #pragma unroll
;       for (int ni = 0; ni < NI; ++ni)
;         acc[mi][ni] = __builtin_amdgcn_mfma_f32_16x16x32_bf16(bfr[ni], af[mi], acc[mi][ni], 0, 0, 0);
;     st = st == 2 ? 0 : st + 1;
;   }
;   asm volatile("s_waitcnt lgkmcnt(0)" ::: "memory");
;   __builtin_amdgcn_s_barrier();
	v_mfma_f32_16x16x32_bf16 v[118:121], v[188:191], v[144:147], v[118:121]
	global_load_lds_dwordx4 v[206:207], off
	v_mfma_f32_16x16x32_bf16 v[102:105], v[188:191], v[148:151], v[102:105]
	v_lshl_add_u64 v[206:207], v[206:207], 0, s[98:99]
	s_add_i32 m0, s12, 0x400
	v_mfma_f32_16x16x32_bf16 v[86:89], v[188:191], v[152:155], v[86:89]
	global_load_lds_dwordx4 v[208:209], off
	v_mfma_f32_16x16x32_bf16 v[70:73], v[188:191], v[156:159], v[70:73]
	v_lshl_add_u64 v[208:209], v[208:209], 0, s[98:99]
	s_waitcnt lgkmcnt(4)
	v_mfma_f32_16x16x32_bf16 v[114:117], v[192:195], v[144:147], v[114:117]
	v_mfma_f32_16x16x32_bf16 v[98:101], v[192:195], v[148:151], v[98:101]
	v_mfma_f32_16x16x32_bf16 v[82:85], v[192:195], v[152:155], v[82:85]
	v_mfma_f32_16x16x32_bf16 v[66:69], v[192:195], v[156:159], v[66:69]
	s_waitcnt lgkmcnt(0)
	v_mfma_f32_16x16x32_bf16 v[62:65], v[180:183], v[164:167], v[62:65]
	v_mfma_f32_16x16x32_bf16 v[46:49], v[180:183], v[168:171], v[46:49]
	v_mfma_f32_16x16x32_bf16 v[30:33], v[180:183], v[172:175], v[30:33]
	v_mfma_f32_16x16x32_bf16 v[14:17], v[180:183], v[176:179], v[14:17]
	v_mfma_f32_16x16x32_bf16 v[58:61], v[184:187], v[164:167], v[58:61]
	v_mfma_f32_16x16x32_bf16 v[42:45], v[184:187], v[168:171], v[42:45]
	v_mfma_f32_16x16x32_bf16 v[26:29], v[184:187], v[172:175], v[26:29]
	v_mfma_f32_16x16x32_bf16 v[10:13], v[184:187], v[176:179], v[10:13]
	v_mfma_f32_16x16x32_bf16 v[54:57], v[188:191], v[164:167], v[54:57]
	v_mfma_f32_16x16x32_bf16 v[38:41], v[188:191], v[168:171], v[38:41]
	v_mfma_f32_16x16x32_bf16 v[22:25], v[188:191], v[172:175], v[22:25]
	v_mfma_f32_16x16x32_bf16 v[6:9], v[188:191], v[176:179], v[6:9]
	v_mfma_f32_16x16x32_bf16 v[50:53], v[192:195], v[164:167], v[50:53]
	v_mfma_f32_16x16x32_bf16 v[34:37], v[192:195], v[168:171], v[34:37]
	v_mfma_f32_16x16x32_bf16 v[18:21], v[192:195], v[172:175], v[18:21]
	v_mfma_f32_16x16x32_bf16 v[2:5], v[192:195], v[176:179], v[2:5]
	s_waitcnt vmcnt(6) lgkmcnt(0)
	s_barrier
	s_setprio 1
	v_add_u32_e32 v0, v140, v142
	ds_read_b128 v[130:133], v0
	ds_read_b128 v[142:145], v0 offset:1024
	ds_read_b128 v[146:149], v0 offset:2048
	ds_read_b128 v[150:153], v0 offset:3072
	ds_read_b128 v[154:157], v0 offset:4096
	ds_read_b128 v[158:161], v0 offset:5120
	ds_read_b128 v[164:167], v0 offset:6144
	ds_read_b128 v[168:171], v0 offset:7168
	v_add_u32_e32 v212, v140, v141
	ds_read_b128 v[138:141], v212 offset:16384
	ds_read_b128 v[172:175], v212 offset:17408
	ds_read_b128 v[176:179], v212 offset:18432
	ds_read_b128 v[180:183], v212 offset:19456
	s_setprio 0
	s_waitcnt vmcnt(0) lgkmcnt(0)
	s_waitcnt lgkmcnt(3)
	v_mfma_f32_16x16x32_bf16 v[126:129], v[138:141], v[130:133], v[126:129]
	s_barrier
	s_waitcnt lgkmcnt(2)
	v_mfma_f32_16x16x32_bf16 v[122:125], v[172:175], v[130:133], v[122:125]
	s_waitcnt lgkmcnt(1)
	v_mfma_f32_16x16x32_bf16 v[184:187], v[176:179], v[130:133], v[118:121]
	s_waitcnt lgkmcnt(0)
	v_mfma_f32_16x16x32_bf16 v[114:117], v[180:183], v[130:133], v[114:117]
	v_mfma_f32_16x16x32_bf16 v[130:133], v[138:141], v[142:145], v[110:113]
	v_mfma_f32_16x16x32_bf16 v[106:109], v[172:175], v[142:145], v[106:109]
	v_mfma_f32_16x16x32_bf16 v[188:191], v[176:179], v[142:145], v[102:105]
	v_mfma_f32_16x16x32_bf16 v[98:101], v[180:183], v[142:145], v[98:101]
	v_mfma_f32_16x16x32_bf16 v[94:97], v[138:141], v[146:149], v[94:97]
	v_mfma_f32_16x16x32_bf16 v[90:93], v[172:175], v[146:149], v[90:93]
	v_mfma_f32_16x16x32_bf16 v[142:145], v[176:179], v[146:149], v[86:89]
	v_mfma_f32_16x16x32_bf16 v[82:85], v[180:183], v[146:149], v[82:85]
	v_mfma_f32_16x16x32_bf16 v[146:149], v[138:141], v[150:153], v[78:81]
	v_mfma_f32_16x16x32_bf16 v[74:77], v[172:175], v[150:153], v[74:77]
	v_mfma_f32_16x16x32_bf16 v[192:195], v[176:179], v[150:153], v[70:73]
	v_mfma_f32_16x16x32_bf16 v[66:69], v[180:183], v[150:153], v[66:69]
	v_mfma_f32_16x16x32_bf16 v[62:65], v[138:141], v[154:157], v[62:65]
	v_mfma_f32_16x16x32_bf16 v[58:61], v[172:175], v[154:157], v[58:61]
	v_mfma_f32_16x16x32_bf16 v[150:153], v[176:179], v[154:157], v[54:57]
	v_mfma_f32_16x16x32_bf16 v[50:53], v[180:183], v[154:157], v[50:53]
	v_mfma_f32_16x16x32_bf16 v[154:157], v[138:141], v[158:161], v[46:49]
	v_mfma_f32_16x16x32_bf16 v[42:45], v[172:175], v[158:161], v[42:45]
	v_mfma_f32_16x16x32_bf16 v[196:199], v[176:179], v[158:161], v[38:41]
	v_mfma_f32_16x16x32_bf16 v[34:37], v[180:183], v[158:161], v[34:37]
	v_mfma_f32_16x16x32_bf16 v[30:33], v[138:141], v[164:167], v[30:33]
	v_mfma_f32_16x16x32_bf16 v[26:29], v[172:175], v[164:167], v[26:29]
	v_mfma_f32_16x16x32_bf16 v[158:161], v[176:179], v[164:167], v[22:25]
	v_mfma_f32_16x16x32_bf16 v[18:21], v[180:183], v[164:167], v[18:21]
	v_mfma_f32_16x16x32_bf16 v[138:141], v[138:141], v[168:171], v[14:17]
	v_mfma_f32_16x16x32_bf16 v[10:13], v[172:175], v[168:171], v[10:13]
	v_mfma_f32_16x16x32_bf16 v[164:167], v[176:179], v[168:171], v[6:9]
	v_mfma_f32_16x16x32_bf16 v[2:5], v[180:183], v[168:171], v[2:5]
	s_setprio 1
	s_nop 0
	ds_read_b128 v[6:9], v0 offset:24576
	ds_read_b128 v[14:17], v0 offset:25600
	ds_read_b128 v[22:25], v0 offset:26624
	ds_read_b128 v[38:41], v0 offset:27648
	ds_read_b128 v[168:171], v0 offset:28672
	ds_read_b128 v[172:175], v0 offset:29696
	ds_read_b128 v[176:179], v0 offset:30720
	ds_read_b128 v[180:183], v0 offset:31744
	ds_read_b128 v[200:203], v212 offset:40960
	ds_read_b128 v[204:207], v212 offset:41984
	ds_read_b128 v[208:211], v212 offset:43008
	ds_read_b128 v[212:215], v212 offset:44032
	s_setprio 0
	s_waitcnt lgkmcnt(3)
	v_mfma_f32_16x16x32_bf16 v[216:219], v[200:203], v[6:9], v[126:129]
	v_mov_b32_e32 v0, v136
	s_waitcnt lgkmcnt(0)
	s_barrier
; DI unsigned pack2(float a, float b) { float2_t v = {a, b}; bf16x2_t r = __builtin_convertvector(v, bf16x2_t); return __builtin_bit_cast(unsigned, r); }
; #define EPI_BEGIN const int lr1_ = launder_v(lr), lq1_ = launder_v(lq), wr1_ = launder_v(wr), wc1_ = launder_v(wc); { const int lr = lr1_, lq = lq1_, wr = wr1_, wc = wc1_; (void)lr; (void)lq; (void)wr; (void)wc;
; DI void phase_mlp1(const Params& p, int l, int Mout, char* smem) {
;     ...
;     EPI_BEGIN
; #pragma unroll
;     for (int mi = 0; mi < 8; mi += 2) {
;       const int m = m0 + wr * 128 + (mi + (lq & 1)) * 16 + lr;
; #pragma unroll
;       for (int ni = 0; ni < 4; ++ni) {
;         const int n = n0 + wc * 64 + ni * 16 + (lq >> 1) * 8;
;         float va[4], vb[4];
; #pragma unroll
;         for (int j = 0; j < 4; ++j) { const float a = fmaxf(acc[mi][ni][j], 0.f); va[j] = a * a; const float b = fmaxf(acc[mi + 1][ni][j], 0.f); vb[j] = b * b; }
;         *(uint4*)(U + (size_t)m * DFF + n) = widen16(make_uint2(pack2(va[0], va[1]), pack2(va[2], va[3])), make_uint2(pack2(vb[0], vb[1]), pack2(vb[2], vb[3])));
;       }
;       __builtin_amdgcn_sched_barrier(0);
;     }
	s_waitcnt lgkmcnt(2)
	v_mfma_f32_16x16x32_bf16 v[118:121], v[204:207], v[6:9], v[122:125]
	v_mov_b32_e32 v126, v137
	v_mov_b32_e32 v127, v134
	v_lshlrev_b32_e32 v129, 2, v126
	v_lshlrev_b32_e32 v126, 4, v126
	v_mfma_f32_16x16x32_bf16 v[122:125], v[200:203], v[14:17], v[130:133]
	v_mov_b32_e32 v128, v135
	v_lshlrev_b32_e32 v127, 7, v127
	v_add_u32_e32 v0, s10, v0
	v_and_b32_e32 v126, 16, v126
	v_add3_u32 v126, v0, v127, v126
	v_lshlrev_b32_e32 v128, 6, v128
	v_and_b32_e32 v129, -8, v129
	v_ashrrev_i32_e32 v127, 31, v126
	v_add3_u32 v132, v129, s9, v128
	v_and_b32_e32 v220, 1, v126
	v_lshrrev_b32_e32 v128, 1, v126
	v_mov_b32_e32 v129, 0
	v_lshlrev_b64 v[128:129], 14, v[128:129]
	v_lshl_or_b32 v128, v220, 6, v128
	v_max_f32_e32 v0, v216, v216
	v_mfma_f32_16x16x32_bf16 v[94:97], v[200:203], v[22:25], v[94:97]
	v_ashrrev_i32_e32 v133, 31, v132
	v_mfma_f32_16x16x32_bf16 v[86:89], v[204:207], v[22:25], v[90:93]
	s_waitcnt lgkmcnt(1)
	v_mfma_f32_16x16x32_bf16 v[78:81], v[208:211], v[22:25], v[142:145]
	s_waitcnt lgkmcnt(0)
	v_mfma_f32_16x16x32_bf16 v[70:73], v[212:215], v[22:25], v[82:85]
	v_mfma_f32_16x16x32_bf16 v[22:25], v[204:207], v[176:179], v[26:29]
	v_mfma_f32_16x16x32_bf16 v[26:29], v[200:203], v[180:183], v[138:141]
	s_nop 2
	v_lshl_add_u64 v[138:139], s[60:61], 0, v[128:129]
	v_max_f32_e32 v128, 0, v0
	v_max_f32_e32 v0, v122, v122
	v_max_f32_e32 v122, 0, v0
	v_max_f32_e32 v0, v217, v217
	v_max_f32_e32 v129, 0, v0
	v_max_f32_e32 v0, v123, v123
	v_max_f32_e32 v123, 0, v0
	v_max_f32_e32 v0, v218, v218
	v_mfma_f32_16x16x32_bf16 v[102:105], v[212:215], v[6:9], v[114:117]
	v_max_f32_e32 v130, 0, v0
	v_max_f32_e32 v0, v124, v124
	v_max_f32_e32 v124, 0, v0
	v_mfma_f32_16x16x32_bf16 v[114:117], v[204:207], v[14:17], v[106:109]
	v_max_f32_e32 v0, v219, v219
	v_max_f32_e32 v131, 0, v0
	v_max_f32_e32 v0, v125, v125
	v_max_f32_e32 v125, 0, v0
	v_max_f32_e32 v0, v118, v118
	v_max_f32_e32 v118, 0, v0
	s_nop 1
	v_max_f32_e32 v0, v114, v114
	v_pk_mul_f32 v[128:129], v[128:129], v[128:129]
	v_pk_mul_f32 v[122:123], v[122:123], v[122:123]
	v_pk_mul_f32 v[130:131], v[130:131], v[130:131]
	v_pk_mul_f32 v[124:125], v[124:125], v[124:125]
	v_max_f32_e32 v114, 0, v0
	v_max_f32_e32 v0, v119, v119
	v_cvt_pk_bf16_f32 v128, v128, v129
	v_cvt_pk_bf16_f32 v129, v130, v131
	v_cvt_pk_bf16_f32 v130, v122, v123
	v_cvt_pk_bf16_f32 v131, v124, v125
	v_and_b32_e32 v220, 31, v132
	v_lshrrev_b32_e32 v122, 5, v132
	v_lshlrev_b32_e32 v122, 7, v122
	v_lshl_or_b32 v122, v220, 1, v122
	v_mov_b32_e32 v123, 0
	v_max_f32_e32 v119, 0, v0
	v_max_f32_e32 v0, v115, v115
	v_mfma_f32_16x16x32_bf16 v[110:113], v[208:211], v[6:9], v[184:187]
	v_permlane16_swap_b32_e32 v128, v130
	v_permlane16_swap_b32_e32 v129, v131
	v_lshl_add_u64 v[124:125], v[138:139], 0, v[122:123]
	v_max_f32_e32 v115, 0, v0
	v_max_f32_e32 v0, v120, v120
	v_mfma_f32_16x16x32_bf16 v[106:109], v[208:211], v[14:17], v[188:191]
	flat_store_dwordx4 v[124:125], v[128:131]
	v_pk_mul_f32 v[118:119], v[118:119], v[118:119]
	s_nop 0
	v_pk_mul_f32 v[128:129], v[114:115], v[114:115]
	v_max_f32_e32 v114, 0, v0
	v_max_f32_e32 v0, v116, v116
	v_max_f32_e32 v116, 0, v0
	v_max_f32_e32 v0, v121, v121
	v_max_f32_e32 v115, 0, v0
	v_max_f32_e32 v0, v117, v117
	v_max_f32_e32 v117, 0, v0
	v_max_f32_e32 v0, v110, v110
	v_max_f32_e32 v110, 0, v0
	v_max_f32_e32 v0, v106, v106
	v_pk_mul_f32 v[120:121], v[114:115], v[114:115]
	v_pk_mul_f32 v[130:131], v[116:117], v[116:117]
	v_max_f32_e32 v106, 0, v0
	v_max_f32_e32 v0, v111, v111
	v_cvt_pk_bf16_f32 v114, v118, v119
	v_cvt_pk_bf16_f32 v115, v120, v121
	v_cvt_pk_bf16_f32 v116, v128, v129
	v_cvt_pk_bf16_f32 v117, v130, v131
	v_max_f32_e32 v111, 0, v0
	v_max_f32_e32 v0, v107, v107
	v_permlane16_swap_b32_e32 v114, v116
	v_permlane16_swap_b32_e32 v115, v117
	v_max_f32_e32 v107, 0, v0
	v_max_f32_e32 v0, v112, v112
	v_mfma_f32_16x16x32_bf16 v[98:101], v[212:215], v[14:17], v[98:101]
	flat_store_dwordx4 v[124:125], v[114:117] offset:32
	v_pk_mul_f32 v[110:111], v[110:111], v[110:111]
	s_nop 0
	v_pk_mul_f32 v[114:115], v[106:107], v[106:107]
	v_max_f32_e32 v106, 0, v0
	v_max_f32_e32 v0, v108, v108
	v_max_f32_e32 v108, 0, v0
	v_max_f32_e32 v0, v113, v113
	v_max_f32_e32 v107, 0, v0
	v_max_f32_e32 v0, v109, v109
	v_max_f32_e32 v109, 0, v0
	v_max_f32_e32 v0, v102, v102
	v_max_f32_e32 v102, 0, v0
	v_max_f32_e32 v0, v98, v98
	v_pk_mul_f32 v[112:113], v[106:107], v[106:107]
	v_pk_mul_f32 v[116:117], v[108:109], v[108:109]
	v_max_f32_e32 v98, 0, v0
	v_max_f32_e32 v0, v103, v103
	v_cvt_pk_bf16_f32 v106, v110, v111
	v_cvt_pk_bf16_f32 v107, v112, v113
	v_cvt_pk_bf16_f32 v108, v114, v115
	v_cvt_pk_bf16_f32 v109, v116, v117
	v_max_f32_e32 v103, 0, v0
	v_max_f32_e32 v0, v99, v99
	v_permlane16_swap_b32_e32 v106, v108
	v_permlane16_swap_b32_e32 v107, v109
	v_max_f32_e32 v99, 0, v0
	v_max_f32_e32 v0, v104, v104
	flat_store_dwordx4 v[124:125], v[106:109] offset:128
	v_pk_mul_f32 v[102:103], v[102:103], v[102:103]
	v_mfma_f32_16x16x32_bf16 v[90:93], v[200:203], v[38:41], v[146:149]
	v_mul_f32_e64 v106, v98, v98
	v_mul_f32_e64 v107, v99, v99
	v_max_f32_e32 v98, 0, v0
	v_max_f32_e32 v0, v100, v100
	v_max_f32_e32 v100, 0, v0
	v_max_f32_e32 v0, v105, v105
	v_max_f32_e32 v99, 0, v0
	v_max_f32_e32 v0, v101, v101
	v_max_f32_e32 v101, 0, v0
	v_pk_mul_f32 v[104:105], v[98:99], v[98:99]
	v_pk_mul_f32 v[108:109], v[100:101], v[100:101]
	v_cvt_pk_bf16_f32 v98, v102, v103
	v_cvt_pk_bf16_f32 v99, v104, v105
	v_cvt_pk_bf16_f32 v100, v106, v107
	v_cvt_pk_bf16_f32 v101, v108, v109
	s_nop 0
	v_permlane16_swap_b32_e32 v98, v100
	v_permlane16_swap_b32_e32 v99, v101
	v_mfma_f32_16x16x32_bf16 v[82:85], v[204:207], v[38:41], v[74:77]
; DI unsigned pack2(float a, float b) { float2_t v = {a, b}; bf16x2_t r = __builtin_convertvector(v, bf16x2_t); return __builtin_bit_cast(unsigned, r); }
; #define EPI_BEGIN const int lr1_ = launder_v(lr), lq1_ = launder_v(lq), wr1_ = launder_v(wr), wc1_ = launder_v(wc); { const int lr = lr1_, lq = lq1_, wr = wr1_, wc = wc1_; (void)lr; (void)lq; (void)wr; (void)wc;
; DI void phase_mlp1(const Params& p, int l, int Mout, char* smem) {
;     ...
;     EPI_BEGIN
; #pragma unroll
;     for (int mi = 0; mi < 8; mi += 2) {
;       const int m = m0 + wr * 128 + (mi + (lq & 1)) * 16 + lr;
; #pragma unroll
;       for (int ni = 0; ni < 4; ++ni) {
;         const int n = n0 + wc * 64 + ni * 16 + (lq >> 1) * 8;
;         float va[4], vb[4];
; #pragma unroll
;         for (int j = 0; j < 4; ++j) { const float a = fmaxf(acc[mi][ni][j], 0.f); va[j] = a * a; const float b = fmaxf(acc[mi + 1][ni][j], 0.f); vb[j] = b * b; }
;         *(uint4*)(U + (size_t)m * DFF + n) = widen16(make_uint2(pack2(va[0], va[1]), pack2(va[2], va[3])), make_uint2(pack2(vb[0], vb[1]), pack2(vb[2], vb[3])));
;       }
;       __builtin_amdgcn_sched_barrier(0);
;     }
	flat_store_dwordx4 v[124:125], v[98:101] offset:160
	v_mfma_f32_16x16x32_bf16 v[74:77], v[208:211], v[38:41], v[192:195]
	v_mfma_f32_16x16x32_bf16 v[66:69], v[212:215], v[38:41], v[66:69]
	v_mfma_f32_16x16x32_bf16 v[62:65], v[200:203], v[168:171], v[62:65]
	v_mfma_f32_16x16x32_bf16 v[54:57], v[204:207], v[168:171], v[58:61]
	v_mfma_f32_16x16x32_bf16 v[46:49], v[208:211], v[168:171], v[150:153]
	v_mfma_f32_16x16x32_bf16 v[38:41], v[212:215], v[168:171], v[50:53]
	v_mfma_f32_16x16x32_bf16 v[58:61], v[200:203], v[172:175], v[154:157]
	v_mfma_f32_16x16x32_bf16 v[50:53], v[204:207], v[172:175], v[42:45]
	v_mfma_f32_16x16x32_bf16 v[42:45], v[208:211], v[172:175], v[196:199]
	v_mfma_f32_16x16x32_bf16 v[34:37], v[212:215], v[172:175], v[34:37]
	v_mfma_f32_16x16x32_bf16 v[30:33], v[200:203], v[176:179], v[30:33]
	v_mfma_f32_16x16x32_bf16 v[14:17], v[208:211], v[176:179], v[158:161]
	v_mfma_f32_16x16x32_bf16 v[6:9], v[212:215], v[176:179], v[18:21]
	v_mfma_f32_16x16x32_bf16 v[18:21], v[204:207], v[180:183], v[10:13]
	v_mfma_f32_16x16x32_bf16 v[10:13], v[208:211], v[180:183], v[164:167]
	v_mfma_f32_16x16x32_bf16 v[2:5], v[212:215], v[180:183], v[2:5]
	v_max_f32_e32 v0, v94, v94
	v_max_f32_e32 v94, 0, v0
	v_max_f32_e32 v0, v90, v90
	v_max_f32_e32 v90, 0, v0
	v_max_f32_e32 v0, v95, v95
	v_max_f32_e32 v95, 0, v0
	v_max_f32_e32 v0, v91, v91
	v_max_f32_e32 v91, 0, v0
	v_max_f32_e32 v0, v96, v96
	v_pk_mul_f32 v[100:101], v[90:91], v[90:91]
	v_max_f32_e32 v90, 0, v0
	v_max_f32_e32 v0, v92, v92
	v_max_f32_e32 v92, 0, v0
	v_max_f32_e32 v0, v97, v97
	v_max_f32_e32 v91, 0, v0
	v_max_f32_e32 v0, v93, v93
	v_add_u32_e32 v98, 32, v126
	v_max_f32_e32 v93, 0, v0
	v_max_f32_e32 v0, v86, v86
	v_ashrrev_i32_e32 v99, 31, v98
	v_max_f32_e32 v86, 0, v0
	v_max_f32_e32 v0, v82, v82
	v_and_b32_e32 v220, 1, v98
	v_lshrrev_b32_e32 v98, 1, v98
	v_mov_b32_e32 v99, 0
	v_lshlrev_b64 v[98:99], 14, v[98:99]
	v_lshl_or_b32 v98, v220, 6, v98
	v_pk_mul_f32 v[94:95], v[94:95], v[94:95]
	v_pk_mul_f32 v[96:97], v[90:91], v[90:91]
	v_pk_mul_f32 v[102:103], v[92:93], v[92:93]
	v_max_f32_e32 v82, 0, v0
	v_max_f32_e32 v0, v87, v87
	v_lshl_add_u64 v[98:99], s[60:61], 0, v[98:99]
	v_cvt_pk_bf16_f32 v90, v94, v95
	v_cvt_pk_bf16_f32 v91, v96, v97
	v_cvt_pk_bf16_f32 v92, v100, v101
	v_cvt_pk_bf16_f32 v93, v102, v103
	v_max_f32_e32 v87, 0, v0
	v_max_f32_e32 v0, v83, v83
	v_permlane16_swap_b32_e32 v90, v92
	v_permlane16_swap_b32_e32 v91, v93
	v_lshl_add_u64 v[94:95], v[98:99], 0, v[122:123]
	v_max_f32_e32 v83, 0, v0
	v_max_f32_e32 v0, v88, v88
	flat_store_dwordx4 v[94:95], v[90:93]
	v_pk_mul_f32 v[86:87], v[86:87], v[86:87]
	s_nop 0
	v_pk_mul_f32 v[90:91], v[82:83], v[82:83]
	v_max_f32_e32 v82, 0, v0
	v_max_f32_e32 v0, v84, v84
	v_max_f32_e32 v84, 0, v0
	v_max_f32_e32 v0, v89, v89
	v_max_f32_e32 v83, 0, v0
	v_max_f32_e32 v0, v85, v85
	v_max_f32_e32 v85, 0, v0
	v_max_f32_e32 v0, v78, v78
	v_max_f32_e32 v78, 0, v0
	v_max_f32_e32 v0, v74, v74
	v_pk_mul_f32 v[88:89], v[82:83], v[82:83]
	v_pk_mul_f32 v[92:93], v[84:85], v[84:85]
	v_max_f32_e32 v74, 0, v0
	v_max_f32_e32 v0, v79, v79
	v_cvt_pk_bf16_f32 v82, v86, v87
	v_cvt_pk_bf16_f32 v83, v88, v89
	v_cvt_pk_bf16_f32 v84, v90, v91
	v_cvt_pk_bf16_f32 v85, v92, v93
	v_max_f32_e32 v79, 0, v0
	v_max_f32_e32 v0, v75, v75
	v_permlane16_swap_b32_e32 v82, v84
	v_permlane16_swap_b32_e32 v83, v85
	v_max_f32_e32 v75, 0, v0
	v_max_f32_e32 v0, v80, v80
	flat_store_dwordx4 v[94:95], v[82:85] offset:32
	v_pk_mul_f32 v[78:79], v[78:79], v[78:79]
	s_nop 0
	v_pk_mul_f32 v[82:83], v[74:75], v[74:75]
	v_max_f32_e32 v74, 0, v0
	v_max_f32_e32 v0, v76, v76
	v_max_f32_e32 v76, 0, v0
	v_max_f32_e32 v0, v81, v81
	v_max_f32_e32 v75, 0, v0
	v_max_f32_e32 v0, v77, v77
	v_max_f32_e32 v77, 0, v0
	v_max_f32_e32 v0, v70, v70
	v_max_f32_e32 v70, 0, v0
	v_max_f32_e32 v0, v66, v66
	v_pk_mul_f32 v[80:81], v[74:75], v[74:75]
	v_pk_mul_f32 v[84:85], v[76:77], v[76:77]
	v_max_f32_e32 v66, 0, v0
	v_max_f32_e32 v0, v71, v71
	v_cvt_pk_bf16_f32 v74, v78, v79
	v_cvt_pk_bf16_f32 v75, v80, v81
	v_cvt_pk_bf16_f32 v76, v82, v83
	v_cvt_pk_bf16_f32 v77, v84, v85
	v_max_f32_e32 v71, 0, v0
	v_max_f32_e32 v0, v67, v67
	v_permlane16_swap_b32_e32 v74, v76
	v_permlane16_swap_b32_e32 v75, v77
	v_max_f32_e32 v67, 0, v0
	v_max_f32_e32 v0, v72, v72
	flat_store_dwordx4 v[94:95], v[74:77] offset:128
	v_pk_mul_f32 v[70:71], v[70:71], v[70:71]
	s_nop 0
	v_pk_mul_f32 v[74:75], v[66:67], v[66:67]
	v_max_f32_e32 v66, 0, v0
	v_max_f32_e32 v0, v68, v68
	v_max_f32_e32 v68, 0, v0
	v_max_f32_e32 v0, v73, v73
	v_max_f32_e32 v67, 0, v0
	v_max_f32_e32 v0, v69, v69
	v_max_f32_e32 v69, 0, v0
	v_pk_mul_f32 v[72:73], v[66:67], v[66:67]
	v_pk_mul_f32 v[76:77], v[68:69], v[68:69]
	v_cvt_pk_bf16_f32 v66, v70, v71
	v_cvt_pk_bf16_f32 v67, v72, v73
	v_cvt_pk_bf16_f32 v68, v74, v75
	v_cvt_pk_bf16_f32 v69, v76, v77
	s_nop 0
	v_permlane16_swap_b32_e32 v66, v68
	v_permlane16_swap_b32_e32 v67, v69
	flat_store_dwordx4 v[94:95], v[66:69] offset:160
	v_max_f32_e32 v0, v62, v62
	v_max_f32_e32 v62, 0, v0
	v_max_f32_e32 v0, v58, v58
	v_max_f32_e32 v58, 0, v0
	v_max_f32_e32 v0, v63, v63
	v_max_f32_e32 v63, 0, v0
	v_max_f32_e32 v0, v59, v59
	v_max_f32_e32 v59, 0, v0
	v_max_f32_e32 v0, v64, v64
	v_pk_mul_f32 v[68:69], v[58:59], v[58:59]
	v_max_f32_e32 v58, 0, v0
	v_max_f32_e32 v0, v60, v60
	v_max_f32_e32 v60, 0, v0
	v_max_f32_e32 v0, v65, v65
	v_max_f32_e32 v59, 0, v0
	v_max_f32_e32 v0, v61, v61
	v_add_u32_e32 v66, 64, v126
	v_max_f32_e32 v61, 0, v0
	v_max_f32_e32 v0, v54, v54
	v_ashrrev_i32_e32 v67, 31, v66
	v_max_f32_e32 v54, 0, v0
	v_max_f32_e32 v0, v50, v50
	v_and_b32_e32 v220, 1, v66
	v_lshrrev_b32_e32 v66, 1, v66
	v_mov_b32_e32 v67, 0
; DI unsigned pack2(float a, float b) { float2_t v = {a, b}; bf16x2_t r = __builtin_convertvector(v, bf16x2_t); return __builtin_bit_cast(unsigned, r); }
; #define EPI_BEGIN const int lr1_ = launder_v(lr), lq1_ = launder_v(lq), wr1_ = launder_v(wr), wc1_ = launder_v(wc); { const int lr = lr1_, lq = lq1_, wr = wr1_, wc = wc1_; (void)lr; (void)lq; (void)wr; (void)wc;
; DI void phase_mlp1(const Params& p, int l, int Mout, char* smem) {
;     ...
;   for (int it = 0;; ++it) {
;     int tm, tn;
;     if (!tile_map(it, ntm, 32, blk__, gridDim.x, tm, tn)) break;
;     const int m0 = tm * 256, n0 = tn * 128;
;     f32x4 acc[8][4]; zero_accm<8, 4>(acc);
;     gemm256<8, 4>(acc, hb, 1024, (const u16*)(wl + WO_W1), 1024, 1024, m0, n0, smem);
;     EPI_BEGIN
; #pragma unroll
;     for (int mi = 0; mi < 8; mi += 2) {
;       const int m = m0 + wr * 128 + (mi + (lq & 1)) * 16 + lr;
; #pragma unroll
;       for (int ni = 0; ni < 4; ++ni) {
;         const int n = n0 + wc * 64 + ni * 16 + (lq >> 1) * 8;
;         float va[4], vb[4];
; #pragma unroll
;         for (int j = 0; j < 4; ++j) { const float a = fmaxf(acc[mi][ni][j], 0.f); va[j] = a * a; const float b = fmaxf(acc[mi + 1][ni][j], 0.f); vb[j] = b * b; }
;         *(uint4*)(U + (size_t)m * DFF + n) = widen16(make_uint2(pack2(va[0], va[1]), pack2(va[2], va[3])), make_uint2(pack2(vb[0], vb[1]), pack2(vb[2], vb[3])));
;       }
;       __builtin_amdgcn_sched_barrier(0);
;     }
	v_lshlrev_b64 v[66:67], 14, v[66:67]
	v_lshl_or_b32 v66, v220, 6, v66
	v_pk_mul_f32 v[62:63], v[62:63], v[62:63]
	v_pk_mul_f32 v[64:65], v[58:59], v[58:59]
	v_pk_mul_f32 v[70:71], v[60:61], v[60:61]
	v_max_f32_e32 v50, 0, v0
	v_max_f32_e32 v0, v55, v55
	v_lshl_add_u64 v[66:67], s[60:61], 0, v[66:67]
	v_cvt_pk_bf16_f32 v58, v62, v63
	v_cvt_pk_bf16_f32 v59, v64, v65
	v_cvt_pk_bf16_f32 v60, v68, v69
	v_cvt_pk_bf16_f32 v61, v70, v71
	v_max_f32_e32 v55, 0, v0
	v_max_f32_e32 v0, v51, v51
	v_permlane16_swap_b32_e32 v58, v60
	v_permlane16_swap_b32_e32 v59, v61
	v_lshl_add_u64 v[62:63], v[66:67], 0, v[122:123]
	v_max_f32_e32 v51, 0, v0
	v_max_f32_e32 v0, v56, v56
	flat_store_dwordx4 v[62:63], v[58:61]
	v_pk_mul_f32 v[54:55], v[54:55], v[54:55]
	s_nop 0
	v_pk_mul_f32 v[58:59], v[50:51], v[50:51]
	v_max_f32_e32 v50, 0, v0
	v_max_f32_e32 v0, v52, v52
	v_max_f32_e32 v52, 0, v0
	v_max_f32_e32 v0, v57, v57
	v_max_f32_e32 v51, 0, v0
	v_max_f32_e32 v0, v53, v53
	v_max_f32_e32 v53, 0, v0
	v_max_f32_e32 v0, v46, v46
	v_max_f32_e32 v46, 0, v0
	v_max_f32_e32 v0, v42, v42
	v_pk_mul_f32 v[56:57], v[50:51], v[50:51]
	v_pk_mul_f32 v[60:61], v[52:53], v[52:53]
	v_max_f32_e32 v42, 0, v0
	v_max_f32_e32 v0, v47, v47
	v_cvt_pk_bf16_f32 v50, v54, v55
	v_cvt_pk_bf16_f32 v51, v56, v57
	v_cvt_pk_bf16_f32 v52, v58, v59
	v_cvt_pk_bf16_f32 v53, v60, v61
	v_max_f32_e32 v47, 0, v0
	v_max_f32_e32 v0, v43, v43
	v_permlane16_swap_b32_e32 v50, v52
	v_permlane16_swap_b32_e32 v51, v53
	v_max_f32_e32 v43, 0, v0
	v_max_f32_e32 v0, v48, v48
	flat_store_dwordx4 v[62:63], v[50:53] offset:32
	v_pk_mul_f32 v[46:47], v[46:47], v[46:47]
	s_nop 0
	v_pk_mul_f32 v[50:51], v[42:43], v[42:43]
	v_max_f32_e32 v42, 0, v0
	v_max_f32_e32 v0, v44, v44
	v_max_f32_e32 v44, 0, v0
	v_max_f32_e32 v0, v49, v49
	v_max_f32_e32 v43, 0, v0
	v_max_f32_e32 v0, v45, v45
	v_max_f32_e32 v45, 0, v0
	v_max_f32_e32 v0, v38, v38
	v_max_f32_e32 v38, 0, v0
	v_max_f32_e32 v0, v34, v34
	v_pk_mul_f32 v[48:49], v[42:43], v[42:43]
	v_pk_mul_f32 v[52:53], v[44:45], v[44:45]
	v_max_f32_e32 v34, 0, v0
	v_max_f32_e32 v0, v39, v39
	v_cvt_pk_bf16_f32 v42, v46, v47
	v_cvt_pk_bf16_f32 v43, v48, v49
	v_cvt_pk_bf16_f32 v44, v50, v51
	v_cvt_pk_bf16_f32 v45, v52, v53
	v_max_f32_e32 v39, 0, v0
	v_max_f32_e32 v0, v35, v35
	v_permlane16_swap_b32_e32 v42, v44
	v_permlane16_swap_b32_e32 v43, v45
	v_max_f32_e32 v35, 0, v0
	v_max_f32_e32 v0, v40, v40
	flat_store_dwordx4 v[62:63], v[42:45] offset:128
	v_pk_mul_f32 v[38:39], v[38:39], v[38:39]
	s_nop 0
	v_pk_mul_f32 v[42:43], v[34:35], v[34:35]
	v_max_f32_e32 v34, 0, v0
	v_max_f32_e32 v0, v36, v36
	v_max_f32_e32 v36, 0, v0
	v_max_f32_e32 v0, v41, v41
	v_max_f32_e32 v35, 0, v0
	v_max_f32_e32 v0, v37, v37
	v_max_f32_e32 v37, 0, v0
	v_pk_mul_f32 v[40:41], v[34:35], v[34:35]
	v_pk_mul_f32 v[44:45], v[36:37], v[36:37]
	v_cvt_pk_bf16_f32 v34, v38, v39
	v_cvt_pk_bf16_f32 v35, v40, v41
	v_cvt_pk_bf16_f32 v36, v42, v43
	v_cvt_pk_bf16_f32 v37, v44, v45
	s_nop 0
	v_permlane16_swap_b32_e32 v34, v36
	v_permlane16_swap_b32_e32 v35, v37
	flat_store_dwordx4 v[62:63], v[34:37] offset:160
	v_max_f32_e32 v0, v30, v30
	v_max_f32_e32 v30, 0, v0
	v_max_f32_e32 v0, v26, v26
	v_max_f32_e32 v26, 0, v0
	v_max_f32_e32 v0, v31, v31
	v_max_f32_e32 v31, 0, v0
	v_max_f32_e32 v0, v27, v27
	v_max_f32_e32 v27, 0, v0
	v_max_f32_e32 v0, v32, v32
	v_pk_mul_f32 v[36:37], v[26:27], v[26:27]
	v_max_f32_e32 v26, 0, v0
	v_max_f32_e32 v0, v28, v28
	v_max_f32_e32 v28, 0, v0
	v_max_f32_e32 v0, v33, v33
	v_max_f32_e32 v27, 0, v0
	v_max_f32_e32 v0, v29, v29
	v_add_u32_e32 v34, 0x60, v126
	v_max_f32_e32 v29, 0, v0
	v_max_f32_e32 v0, v22, v22
	v_ashrrev_i32_e32 v35, 31, v34
	v_max_f32_e32 v22, 0, v0
	v_max_f32_e32 v0, v18, v18
	v_and_b32_e32 v220, 1, v34
	v_lshrrev_b32_e32 v34, 1, v34
	v_mov_b32_e32 v35, 0
	v_lshlrev_b64 v[34:35], 14, v[34:35]
	v_lshl_or_b32 v34, v220, 6, v34
	v_pk_mul_f32 v[30:31], v[30:31], v[30:31]
	v_pk_mul_f32 v[32:33], v[26:27], v[26:27]
	v_pk_mul_f32 v[38:39], v[28:29], v[28:29]
	v_max_f32_e32 v18, 0, v0
	v_max_f32_e32 v0, v23, v23
	v_lshl_add_u64 v[34:35], s[60:61], 0, v[34:35]
	v_cvt_pk_bf16_f32 v26, v30, v31
	v_cvt_pk_bf16_f32 v27, v32, v33
	v_cvt_pk_bf16_f32 v28, v36, v37
	v_cvt_pk_bf16_f32 v29, v38, v39
	v_max_f32_e32 v23, 0, v0
	v_max_f32_e32 v0, v19, v19
	v_permlane16_swap_b32_e32 v26, v28
	v_permlane16_swap_b32_e32 v27, v29
	v_lshl_add_u64 v[30:31], v[34:35], 0, v[122:123]
	v_max_f32_e32 v19, 0, v0
	v_max_f32_e32 v0, v24, v24
	flat_store_dwordx4 v[30:31], v[26:29]
	v_pk_mul_f32 v[22:23], v[22:23], v[22:23]
	s_nop 0
	v_pk_mul_f32 v[26:27], v[18:19], v[18:19]
	v_max_f32_e32 v18, 0, v0
	v_max_f32_e32 v0, v20, v20
	v_max_f32_e32 v20, 0, v0
	v_max_f32_e32 v0, v25, v25
	v_max_f32_e32 v19, 0, v0
	v_max_f32_e32 v0, v21, v21
	v_max_f32_e32 v21, 0, v0
	v_max_f32_e32 v0, v14, v14
	v_max_f32_e32 v14, 0, v0
	v_max_f32_e32 v0, v10, v10
	v_pk_mul_f32 v[24:25], v[18:19], v[18:19]
	v_pk_mul_f32 v[28:29], v[20:21], v[20:21]
	v_max_f32_e32 v10, 0, v0
	v_max_f32_e32 v0, v15, v15
	v_cvt_pk_bf16_f32 v18, v22, v23
	v_cvt_pk_bf16_f32 v19, v24, v25
	v_cvt_pk_bf16_f32 v20, v26, v27
	v_cvt_pk_bf16_f32 v21, v28, v29
	v_max_f32_e32 v15, 0, v0
	v_max_f32_e32 v0, v11, v11
	v_permlane16_swap_b32_e32 v18, v20
	v_permlane16_swap_b32_e32 v19, v21
	v_max_f32_e32 v11, 0, v0
	v_max_f32_e32 v0, v16, v16
	flat_store_dwordx4 v[30:31], v[18:21] offset:32
	v_pk_mul_f32 v[14:15], v[14:15], v[14:15]
	s_nop 0
	v_pk_mul_f32 v[18:19], v[10:11], v[10:11]
	v_max_f32_e32 v10, 0, v0
	v_max_f32_e32 v0, v12, v12
	v_max_f32_e32 v12, 0, v0
	v_max_f32_e32 v0, v17, v17
	v_max_f32_e32 v11, 0, v0
	v_max_f32_e32 v0, v13, v13
	v_max_f32_e32 v13, 0, v0
	v_max_f32_e32 v0, v6, v6
	v_max_f32_e32 v6, 0, v0
	v_max_f32_e32 v0, v2, v2
	v_pk_mul_f32 v[16:17], v[10:11], v[10:11]
	v_pk_mul_f32 v[20:21], v[12:13], v[12:13]
	v_max_f32_e32 v2, 0, v0
	v_max_f32_e32 v0, v7, v7
	v_cvt_pk_bf16_f32 v10, v14, v15
	v_cvt_pk_bf16_f32 v11, v16, v17
	v_cvt_pk_bf16_f32 v12, v18, v19
	v_cvt_pk_bf16_f32 v13, v20, v21
	v_max_f32_e32 v7, 0, v0
	v_max_f32_e32 v0, v3, v3
	v_permlane16_swap_b32_e32 v10, v12
	v_permlane16_swap_b32_e32 v11, v13
	v_max_f32_e32 v3, 0, v0
	v_max_f32_e32 v0, v8, v8
	flat_store_dwordx4 v[30:31], v[10:13] offset:128
	v_pk_mul_f32 v[6:7], v[6:7], v[6:7]
	s_nop 0
	v_pk_mul_f32 v[10:11], v[2:3], v[2:3]
	v_max_f32_e32 v2, 0, v0
	v_max_f32_e32 v0, v4, v4
	v_max_f32_e32 v4, 0, v0
	v_max_f32_e32 v0, v9, v9
	v_max_f32_e32 v3, 0, v0
	v_max_f32_e32 v0, v5, v5
	v_max_f32_e32 v5, 0, v0
	v_pk_mul_f32 v[8:9], v[2:3], v[2:3]
	v_pk_mul_f32 v[12:13], v[4:5], v[4:5]
	v_cvt_pk_bf16_f32 v2, v6, v7
	v_cvt_pk_bf16_f32 v3, v8, v9
	v_cvt_pk_bf16_f32 v4, v10, v11
	v_cvt_pk_bf16_f32 v5, v12, v13
	s_nop 0
	v_permlane16_swap_b32_e32 v2, v4
	v_permlane16_swap_b32_e32 v3, v5
	flat_store_dwordx4 v[30:31], v[2:5] offset:160
	s_add_i32 s8, s8, 1
	s_mul_i32 s4, s8, s39
	s_add_i32 s9, s4, s6
	v_readlane_b32 s4, v253, 41
	s_cmp_ge_i32 s9, s4
	s_cbranch_scc0 .LBB0_441

; template <int MI, int NI>
; DI void gemm256(f32x4 (&acc)[MI][NI], const u16* __restrict__ A, int lda, const u16* __restrict__ Bt, int ldb, int K, int m0, int n0, char* smem) {
;     ...
;   for (int kt = 0; kt < nk; ++kt) {
;     if (kt + 1 < nk) asm volatile("s_waitcnt vmcnt(%0) lgkmcnt(0)" :: "n"(LPS) : "memory");
;     else asm volatile("s_waitcnt vmcnt(0) lgkmcnt(0)" ::: "memory");
;     __builtin_amdgcn_s_barrier();
;     __builtin_amdgcn_s_setprio(1);
;     const char* sb = smem + st * STAGE + foff;
;     bf16x8 af[MI], bfr[NI];
; #pragma unroll
;     for (int mi = 0; mi < MI; ++mi) af[mi] = *(const bf16x8*)(sb + (wr * MI + mi) * 1024);
; #pragma unroll
;     for (int ni = 0; ni < NI; ++ni) bfr[ni] = *(const bf16x8*)(sb + ABYTES + (wc * NI + ni) * 1024);
;     __builtin_amdgcn_sched_barrier(0x0);
;     if (kt + 2 < nk) { const int s2 = st >= 1 ? st - 1 : 2; G256_ISSUE(s2, (kt + 2) * 32); }
;     __builtin_amdgcn_s_setprio(0);
; #pragma unroll
;     for (int mi = 0; mi < MI; ++mi)
; #pragma unroll
;       for (int ni = 0; ni < NI; ++ni)
;         acc[mi][ni] = __builtin_amdgcn_mfma_f32_16x16x32_bf16(bfr[ni], af[mi], acc[mi][ni], 0, 0, 0);
;     st = st == 2 ? 0 : st + 1;
;   }
.Lpipe_wo:
	v_add_u32_e32 v161, s12, v160
	ds_read_b128 v[156:159], v161 offset:4096
	ds_read_b128 v[164:167], v161 offset:5120
	ds_read_b128 v[168:171], v161 offset:6144
	ds_read_b128 v[172:175], v161 offset:7168
	s_add_i32 s14, s12, 0xffffa000
	s_cmp_eq_u32 s12, 0
	s_cselect_b32 s14, 0xc000, s14
	s_add_i32 s15, s14, s13
	s_add_i32 s14, s14, s4
	s_mov_b32 m0, s15
	s_waitcnt lgkmcnt(7)
	v_mfma_f32_16x16x32_bf16 v[126:129], v[176:179], v[140:143], v[126:129]
	global_load_lds_dwordx4 v[196:197], off
	v_mfma_f32_16x16x32_bf16 v[110:113], v[176:179], v[144:147], v[110:113]
	v_lshl_add_u64 v[196:197], v[196:197], 0, s[98:99]
	s_add_i32 m0, s15, 0x400
	v_mfma_f32_16x16x32_bf16 v[94:97], v[176:179], v[148:151], v[94:97]
	global_load_lds_dwordx4 v[198:199], off
	v_mfma_f32_16x16x32_bf16 v[78:81], v[176:179], v[152:155], v[78:81]
	v_lshl_add_u64 v[198:199], v[198:199], 0, s[98:99]
	s_add_i32 m0, s15, 0x800
	s_waitcnt lgkmcnt(6)
	v_mfma_f32_16x16x32_bf16 v[122:125], v[180:183], v[140:143], v[122:125]
	global_load_lds_dwordx4 v[200:201], off
	v_mfma_f32_16x16x32_bf16 v[106:109], v[180:183], v[144:147], v[106:109]
	v_lshl_add_u64 v[200:201], v[200:201], 0, s[98:99]
	s_add_i32 m0, s15, 0xc00
	v_mfma_f32_16x16x32_bf16 v[90:93], v[180:183], v[148:151], v[90:93]
	global_load_lds_dwordx4 v[202:203], off
	v_mfma_f32_16x16x32_bf16 v[74:77], v[180:183], v[152:155], v[74:77]
	v_lshl_add_u64 v[202:203], v[202:203], 0, s[98:99]
	s_mov_b32 m0, s14
	s_waitcnt lgkmcnt(5)
	v_mfma_f32_16x16x32_bf16 v[118:121], v[184:187], v[140:143], v[118:121]
	global_load_lds_dwordx4 v[204:205], off
	v_mfma_f32_16x16x32_bf16 v[102:105], v[184:187], v[144:147], v[102:105]
	v_lshl_add_u64 v[204:205], v[204:205], 0, 64
	s_add_i32 m0, s14, 0x400
	v_mfma_f32_16x16x32_bf16 v[86:89], v[184:187], v[148:151], v[86:89]
	global_load_lds_dwordx4 v[206:207], off
	v_mfma_f32_16x16x32_bf16 v[70:73], v[184:187], v[152:155], v[70:73]
	v_lshl_add_u64 v[206:207], v[206:207], 0, 64
	s_waitcnt lgkmcnt(4)
	v_mfma_f32_16x16x32_bf16 v[114:117], v[188:191], v[140:143], v[114:117]
	s_add_i32 s15, s12, 0x6000
	v_mfma_f32_16x16x32_bf16 v[98:101], v[188:191], v[144:147], v[98:101]
	s_cmp_eq_u32 s12, 0xc000
	s_cselect_b32 s12, 0, s15
	v_mfma_f32_16x16x32_bf16 v[82:85], v[188:191], v[148:151], v[82:85]
	v_add_u32_e32 v192, s12, v160
	v_mfma_f32_16x16x32_bf16 v[66:69], v[188:191], v[152:155], v[66:69]
	v_add_u32_e32 v193, s12, v0
	s_waitcnt vmcnt(6) lgkmcnt(0)
	s_barrier
	v_mfma_f32_16x16x32_bf16 v[62:65], v[176:179], v[156:159], v[62:65]
	ds_read_b128 v[140:143], v192
	v_mfma_f32_16x16x32_bf16 v[46:49], v[176:179], v[164:167], v[46:49]
	ds_read_b128 v[144:147], v192 offset:1024
	v_mfma_f32_16x16x32_bf16 v[30:33], v[176:179], v[168:171], v[30:33]
	ds_read_b128 v[148:151], v192 offset:2048
	v_mfma_f32_16x16x32_bf16 v[14:17], v[176:179], v[172:175], v[14:17]
	ds_read_b128 v[152:155], v192 offset:3072
	ds_read_b128 v[176:179], v193 offset:16384
	v_mfma_f32_16x16x32_bf16 v[58:61], v[180:183], v[156:159], v[58:61]
	v_mfma_f32_16x16x32_bf16 v[42:45], v[180:183], v[164:167], v[42:45]
	v_mfma_f32_16x16x32_bf16 v[26:29], v[180:183], v[168:171], v[26:29]
	v_mfma_f32_16x16x32_bf16 v[10:13], v[180:183], v[172:175], v[10:13]
	ds_read_b128 v[180:183], v193 offset:17408
	v_mfma_f32_16x16x32_bf16 v[54:57], v[184:187], v[156:159], v[54:57]
	v_mfma_f32_16x16x32_bf16 v[38:41], v[184:187], v[164:167], v[38:41]
	v_mfma_f32_16x16x32_bf16 v[22:25], v[184:187], v[168:171], v[22:25]
	v_mfma_f32_16x16x32_bf16 v[6:9], v[184:187], v[172:175], v[6:9]
	ds_read_b128 v[184:187], v193 offset:18432
	v_mfma_f32_16x16x32_bf16 v[50:53], v[188:191], v[156:159], v[50:53]
	v_mfma_f32_16x16x32_bf16 v[34:37], v[188:191], v[164:167], v[34:37]
	v_mfma_f32_16x16x32_bf16 v[18:21], v[188:191], v[168:171], v[18:21]
	v_mfma_f32_16x16x32_bf16 v[2:5], v[188:191], v[172:175], v[2:5]
	ds_read_b128 v[188:191], v193 offset:19456
	s_sub_i32 s5, s5, 1
	s_cmp_lg_u32 s5, 0
	s_cbranch_scc1 .Lpipe_wo
	v_add_u32_e32 v161, s12, v160
	ds_read_b128 v[156:159], v161 offset:4096
	ds_read_b128 v[164:167], v161 offset:5120
	ds_read_b128 v[168:171], v161 offset:6144
	ds_read_b128 v[172:175], v161 offset:7168
	s_add_i32 s14, s12, 0xffffa000
	s_cmp_eq_u32 s12, 0
	s_cselect_b32 s14, 0xc000, s14
	s_add_i32 s15, s14, s13
	s_add_i32 s14, s14, s4
	s_mov_b32 m0, s15
	s_waitcnt lgkmcnt(7)
	v_mfma_f32_16x16x32_bf16 v[126:129], v[176:179], v[140:143], v[126:129]
	global_load_lds_dwordx4 v[196:197], off
	v_mfma_f32_16x16x32_bf16 v[110:113], v[176:179], v[144:147], v[110:113]
	v_lshl_add_u64 v[196:197], v[196:197], 0, s[98:99]
	s_add_i32 m0, s15, 0x400
	v_mfma_f32_16x16x32_bf16 v[94:97], v[176:179], v[148:151], v[94:97]
	global_load_lds_dwordx4 v[198:199], off
	v_mfma_f32_16x16x32_bf16 v[78:81], v[176:179], v[152:155], v[78:81]
	v_lshl_add_u64 v[198:199], v[198:199], 0, s[98:99]
	s_add_i32 m0, s15, 0x800
	s_waitcnt lgkmcnt(6)
	v_mfma_f32_16x16x32_bf16 v[122:125], v[180:183], v[140:143], v[122:125]
	global_load_lds_dwordx4 v[200:201], off
	v_mfma_f32_16x16x32_bf16 v[106:109], v[180:183], v[144:147], v[106:109]
	v_lshl_add_u64 v[200:201], v[200:201], 0, s[98:99]
	s_add_i32 m0, s15, 0xc00
	v_mfma_f32_16x16x32_bf16 v[90:93], v[180:183], v[148:151], v[90:93]
	global_load_lds_dwordx4 v[202:203], off
	v_mfma_f32_16x16x32_bf16 v[74:77], v[180:183], v[152:155], v[74:77]
	v_lshl_add_u64 v[202:203], v[202:203], 0, s[98:99]
	s_mov_b32 m0, s14
	s_waitcnt lgkmcnt(5)
; template <int MI, int NI>
; DI void gemm256(f32x4 (&acc)[MI][NI], const u16* __restrict__ A, int lda, const u16* __restrict__ Bt, int ldb, int K, int m0, int n0, char* smem) {
;     ...
;   for (int kt = 0; kt < nk; ++kt) {
;     if (kt + 1 < nk) asm volatile("s_waitcnt vmcnt(%0) lgkmcnt(0)" :: "n"(LPS) : "memory");
;     else asm volatile("s_waitcnt vmcnt(0) lgkmcnt(0)" ::: "memory");
;     __builtin_amdgcn_s_barrier();
;     __builtin_amdgcn_s_setprio(1);
;     const char* sb = smem + st * STAGE + foff;
;     bf16x8 af[MI], bfr[NI];
; #pragma unroll
;     for (int mi = 0; mi < MI; ++mi) af[mi] = *(const bf16x8*)(sb + (wr * MI + mi) * 1024);
; #pragma unroll
;     for (int ni = 0; ni < NI; ++ni) bfr[ni] = *(const bf16x8*)(sb + ABYTES + (wc * NI + ni) * 1024);
;     __builtin_amdgcn_sched_barrier(0x0);
;     if (kt + 2 < nk) { const int s2 = st >= 1 ? st - 1 : 2; G256_ISSUE(s2, (kt + 2) * 32); }
;     __builtin_amdgcn_s_setprio(0);
; #pragma unroll
;     for (int mi = 0; mi < MI; ++mi)
; #pragma unroll
;       for (int ni = 0; ni < NI; ++ni)
;         acc[mi][ni] = __builtin_amdgcn_mfma_f32_16x16x32_bf16(bfr[ni], af[mi], acc[mi][ni], 0, 0, 0);
;     st = st == 2 ? 0 : st + 1;
;   }
;   asm volatile("s_waitcnt lgkmcnt(0)" ::: "memory");
;   __builtin_amdgcn_s_barrier();
	v_mfma_f32_16x16x32_bf16 v[118:121], v[184:187], v[140:143], v[118:121]
	global_load_lds_dwordx4 v[204:205], off
	v_mfma_f32_16x16x32_bf16 v[102:105], v[184:187], v[144:147], v[102:105]
	v_lshl_add_u64 v[204:205], v[204:205], 0, 64
	s_add_i32 m0, s14, 0x400
	v_mfma_f32_16x16x32_bf16 v[86:89], v[184:187], v[148:151], v[86:89]
	global_load_lds_dwordx4 v[206:207], off
	v_mfma_f32_16x16x32_bf16 v[70:73], v[184:187], v[152:155], v[70:73]
	v_lshl_add_u64 v[206:207], v[206:207], 0, 64
	s_waitcnt lgkmcnt(4)
	v_mfma_f32_16x16x32_bf16 v[114:117], v[188:191], v[140:143], v[114:117]
	v_mfma_f32_16x16x32_bf16 v[98:101], v[188:191], v[144:147], v[98:101]
	v_mfma_f32_16x16x32_bf16 v[82:85], v[188:191], v[148:151], v[82:85]
	v_mfma_f32_16x16x32_bf16 v[66:69], v[188:191], v[152:155], v[66:69]
	s_waitcnt lgkmcnt(0)
	v_mfma_f32_16x16x32_bf16 v[62:65], v[176:179], v[156:159], v[62:65]
	v_mfma_f32_16x16x32_bf16 v[46:49], v[176:179], v[164:167], v[46:49]
	v_mfma_f32_16x16x32_bf16 v[30:33], v[176:179], v[168:171], v[30:33]
	v_mfma_f32_16x16x32_bf16 v[14:17], v[176:179], v[172:175], v[14:17]
	v_mfma_f32_16x16x32_bf16 v[58:61], v[180:183], v[156:159], v[58:61]
	v_mfma_f32_16x16x32_bf16 v[42:45], v[180:183], v[164:167], v[42:45]
	v_mfma_f32_16x16x32_bf16 v[26:29], v[180:183], v[168:171], v[26:29]
	v_mfma_f32_16x16x32_bf16 v[10:13], v[180:183], v[172:175], v[10:13]
	v_mfma_f32_16x16x32_bf16 v[54:57], v[184:187], v[156:159], v[54:57]
	v_mfma_f32_16x16x32_bf16 v[38:41], v[184:187], v[164:167], v[38:41]
	v_mfma_f32_16x16x32_bf16 v[22:25], v[184:187], v[168:171], v[22:25]
	v_mfma_f32_16x16x32_bf16 v[6:9], v[184:187], v[172:175], v[6:9]
	v_mfma_f32_16x16x32_bf16 v[50:53], v[188:191], v[156:159], v[50:53]
	v_mfma_f32_16x16x32_bf16 v[34:37], v[188:191], v[164:167], v[34:37]
	v_mfma_f32_16x16x32_bf16 v[18:21], v[188:191], v[168:171], v[18:21]
	v_mfma_f32_16x16x32_bf16 v[2:5], v[188:191], v[172:175], v[2:5]
	s_waitcnt vmcnt(6) lgkmcnt(0)
	s_barrier
	s_setprio 1
	v_add_u32_e32 v0, v137, v139
	ds_read_b128 v[130:133], v0
	ds_read_b128 v[140:143], v0 offset:1024
	ds_read_b128 v[144:147], v0 offset:2048
	ds_read_b128 v[148:151], v0 offset:3072
	ds_read_b128 v[152:155], v0 offset:4096
	ds_read_b128 v[156:159], v0 offset:5120
	ds_read_b128 v[164:167], v0 offset:6144
	ds_read_b128 v[168:171], v0 offset:7168
	v_add_u32_e32 v184, v137, v138
	ds_read_b128 v[136:139], v184 offset:16384
	ds_read_b128 v[172:175], v184 offset:17408
	ds_read_b128 v[176:179], v184 offset:18432
	ds_read_b128 v[180:183], v184 offset:19456
	v_bfe_u32 v188, v134, 6, 1
	s_setprio 0
	s_waitcnt vmcnt(0) lgkmcnt(0)
	s_waitcnt lgkmcnt(3)
	v_mfma_f32_16x16x32_bf16 v[126:129], v[136:139], v[130:133], v[126:129]
	v_ashrrev_i32_e32 v189, 7, v134
	v_and_b32_e32 v190, 15, v134
	v_bfe_u32 v191, v134, 4, 2
	s_waitcnt lgkmcnt(2)
	v_mfma_f32_16x16x32_bf16 v[122:125], v[172:175], v[130:133], v[122:125]
	s_barrier
	s_waitcnt lgkmcnt(1)
	v_mfma_f32_16x16x32_bf16 v[118:121], v[176:179], v[130:133], v[118:121]
	s_waitcnt lgkmcnt(0)
	v_mfma_f32_16x16x32_bf16 v[114:117], v[180:183], v[130:133], v[114:117]
	v_mfma_f32_16x16x32_bf16 v[110:113], v[136:139], v[140:143], v[110:113]
	v_mfma_f32_16x16x32_bf16 v[106:109], v[172:175], v[140:143], v[106:109]
	v_mfma_f32_16x16x32_bf16 v[102:105], v[176:179], v[140:143], v[102:105]
	v_mfma_f32_16x16x32_bf16 v[98:101], v[180:183], v[140:143], v[98:101]
	v_mfma_f32_16x16x32_bf16 v[94:97], v[136:139], v[144:147], v[94:97]
	v_mfma_f32_16x16x32_bf16 v[90:93], v[172:175], v[144:147], v[90:93]
	v_mfma_f32_16x16x32_bf16 v[86:89], v[176:179], v[144:147], v[86:89]
	v_mfma_f32_16x16x32_bf16 v[82:85], v[180:183], v[144:147], v[82:85]
	v_mfma_f32_16x16x32_bf16 v[78:81], v[136:139], v[148:151], v[78:81]
	v_mfma_f32_16x16x32_bf16 v[130:133], v[172:175], v[148:151], v[74:77]
	v_mfma_f32_16x16x32_bf16 v[70:73], v[176:179], v[148:151], v[70:73]
	v_mfma_f32_16x16x32_bf16 v[66:69], v[180:183], v[148:151], v[66:69]
	v_mfma_f32_16x16x32_bf16 v[62:65], v[136:139], v[152:155], v[62:65]
	v_mfma_f32_16x16x32_bf16 v[58:61], v[172:175], v[152:155], v[58:61]
	v_mfma_f32_16x16x32_bf16 v[54:57], v[176:179], v[152:155], v[54:57]
	v_mfma_f32_16x16x32_bf16 v[50:53], v[180:183], v[152:155], v[50:53]
	v_mfma_f32_16x16x32_bf16 v[46:49], v[136:139], v[156:159], v[46:49]
	v_mfma_f32_16x16x32_bf16 v[42:45], v[172:175], v[156:159], v[42:45]
	v_mfma_f32_16x16x32_bf16 v[38:41], v[176:179], v[156:159], v[38:41]
	v_mfma_f32_16x16x32_bf16 v[34:37], v[180:183], v[156:159], v[34:37]
	v_mfma_f32_16x16x32_bf16 v[30:33], v[136:139], v[164:167], v[30:33]
	v_mfma_f32_16x16x32_bf16 v[26:29], v[172:175], v[164:167], v[26:29]
	v_mfma_f32_16x16x32_bf16 v[22:25], v[176:179], v[164:167], v[22:25]
	v_mfma_f32_16x16x32_bf16 v[18:21], v[180:183], v[164:167], v[18:21]
	v_mfma_f32_16x16x32_bf16 v[14:17], v[136:139], v[168:171], v[14:17]
	v_mfma_f32_16x16x32_bf16 v[10:13], v[172:175], v[168:171], v[10:13]
	v_mfma_f32_16x16x32_bf16 v[6:9], v[176:179], v[168:171], v[6:9]
	v_mfma_f32_16x16x32_bf16 v[134:137], v[180:183], v[168:171], v[2:5]
	s_setprio 1
	s_nop 1
	ds_read_b128 v[2:5], v0 offset:24576
	ds_read_b128 v[74:77], v0 offset:25600
	ds_read_b128 v[138:141], v0 offset:26624
	ds_read_b128 v[142:145], v0 offset:27648
	ds_read_b128 v[146:149], v0 offset:28672
	ds_read_b128 v[150:153], v0 offset:29696
	ds_read_b128 v[154:157], v0 offset:30720
	ds_read_b128 v[158:161], v0 offset:31744
	ds_read_b128 v[164:167], v184 offset:40960
	ds_read_b128 v[168:171], v184 offset:41984
	ds_read_b128 v[172:175], v184 offset:43008
	ds_read_b128 v[176:179], v184 offset:44032
	s_setprio 0
	s_waitcnt lgkmcnt(0)
	s_barrier
; #define EPI_BEGIN const int lr1_ = launder_v(lr), lq1_ = launder_v(lq), wr1_ = launder_v(wr), wc1_ = launder_v(wc); { const int lr = lr1_, lq = lq1_, wr = wr1_, wc = wc1_; (void)lr; (void)lq; (void)wr; (void)wc;
; template <int MI, int NI>
; DI void resid_tile(const u16* A, int K, const u16* Bt, const float* gate, const float* xl_in, const float* xc_in, float* xl_out, float* xc_out,
;                    int m0, int n0, char* smem) {
;     ...
;   EPI_BEGIN
; #pragma unroll
;   for (int mi = 0; mi < MI; ++mi) {
;     const int m = m0 + wr * 16 * MI + mi * 16 + lr;
;     const int b9 = m < NTL ? m >> 12 : 8;
;     const float* xi = xrow(xl_in, xc_in, m);
;     float* xo = m < NTL ? xl_out + (size_t)m * D : xc_out + (size_t)(m - NTL) * D;
; #pragma unroll
;     for (int ni = 0; ni < NI; ++ni) {
;       const int n = n0 + wc * 16 * NI + ni * 16 + lq * 4;
;       const float4 g = *(const float4*)(gate + (size_t)b9 * 6144 + n);
;       const float4 xv = *(const float4*)(xi + n);
;       float4 ov;
;       ov.x = xv.x + g.x * acc[mi][ni][0]; ov.y = xv.y + g.y * acc[mi][ni][1]; ov.z = xv.z + g.z * acc[mi][ni][2]; ov.w = xv.w + g.w * acc[mi][ni][3];
;       *(float4*)(xo + n) = ov;
;     }
	v_readlane_b32 s4, v253, 55
	v_lshlrev_b32_e32 v0, 7, v189
	s_waitcnt lgkmcnt(3)
	v_mfma_f32_16x16x32_bf16 v[126:129], v[164:167], v[2:5], v[126:129]
	s_waitcnt lgkmcnt(2)
	v_mfma_f32_16x16x32_bf16 v[122:125], v[168:171], v[2:5], v[122:125]
	s_waitcnt lgkmcnt(1)
	v_mfma_f32_16x16x32_bf16 v[180:183], v[172:175], v[2:5], v[118:121]
	s_waitcnt lgkmcnt(0)
	v_mfma_f32_16x16x32_bf16 v[184:187], v[176:179], v[2:5], v[114:117]
	v_lshlrev_b32_e32 v2, 2, v191
	v_mov_b32_e32 v118, s4
	v_readlane_b32 s4, v253, 53
	v_add3_u32 v116, v190, s10, v0
	v_lshlrev_b32_e32 v0, 6, v188
	v_add3_u32 v2, v2, s11, v0
	v_min_i32_e32 v0, 0x8000, v116
	v_mov_b32_e32 v119, s4
	v_readlane_b32 s4, v253, 56
	v_mfma_f32_16x16x32_bf16 v[110:113], v[164:167], v[74:77], v[110:113]
	v_ashrrev_i32_e32 v117, 31, v116
	v_cmp_gt_i32_e32 vcc, s58, v116
	v_mov_b32_e32 v120, s4
	v_mfma_f32_16x16x32_bf16 v[106:109], v[168:171], v[74:77], v[106:109]
	v_readlane_b32 s4, v253, 54
	v_cndmask_b32_e32 v5, 0, v117, vcc
	v_cndmask_b32_e32 v115, v118, v119, vcc
	v_mfma_f32_16x16x32_bf16 v[102:105], v[172:175], v[74:77], v[102:105]
	v_mov_b32_e32 v121, s4
	v_cndmask_b32_e32 v114, v120, v121, vcc
	v_readlane_b32 s4, v253, 51
	v_mfma_f32_16x16x32_bf16 v[98:101], v[176:179], v[74:77], v[98:101]
	v_ashrrev_i32_e32 v3, 31, v2
	v_readlane_b32 s5, v253, 52
	v_mfma_f32_16x16x32_bf16 v[74:77], v[164:167], v[142:145], v[78:81]
	v_mfma_f32_16x16x32_bf16 v[78:81], v[168:171], v[142:145], v[130:133]
	s_nop 2
	v_ashrrev_i32_e32 v130, 12, v0
	v_add_u32_e32 v0, 0xffff8000, v116
	v_cndmask_b32_e32 v4, v0, v116, vcc
	v_lshlrev_b64 v[4:5], 12, v[4:5]
	v_lshl_add_u64 v[4:5], v[114:115], 0, v[4:5]
	v_mul_hi_i32_i24_e32 v115, 0x6000, v130
	v_mul_i32_i24_e32 v114, 0x6000, v130
	v_lshl_add_u64 v[130:131], s[4:5], 0, v[114:115]
	v_lshlrev_b64 v[114:115], 2, v[2:3]
	v_mfma_f32_16x16x32_bf16 v[94:97], v[164:167], v[138:141], v[94:97]
	v_mfma_f32_16x16x32_bf16 v[90:93], v[168:171], v[138:141], v[90:93]
	v_mfma_f32_16x16x32_bf16 v[86:89], v[172:175], v[138:141], v[86:89]
	v_mfma_f32_16x16x32_bf16 v[82:85], v[176:179], v[138:141], v[82:85]
	v_lshl_add_u64 v[138:139], v[130:131], 0, v[114:115]
	v_lshl_add_u64 v[140:141], v[4:5], 0, v[114:115]
	flat_load_dwordx4 v[2:5], v[138:139]
	flat_load_dwordx4 v[130:133], v[140:141]
	v_mfma_f32_16x16x32_bf16 v[70:73], v[172:175], v[142:145], v[70:73]
	s_waitcnt vmcnt(0) lgkmcnt(0)
	v_pk_fma_f32 v[2:3], v[126:127], v[2:3], v[130:131]
	v_mfma_f32_16x16x32_bf16 v[66:69], v[176:179], v[142:145], v[66:69]
	v_lshlrev_b64 v[142:143], 12, v[116:117]
	v_lshlrev_b64 v[144:145], 12, v[0:1]
	v_lshl_add_u64 v[142:143], s[48:49], 0, v[142:143]
	v_lshl_add_u64 v[144:145], s[94:95], 0, v[144:145]
	v_cndmask_b32_e32 v143, v145, v143, vcc
	v_cndmask_b32_e32 v142, v144, v142, vcc
	v_lshl_add_u64 v[142:143], v[142:143], 0, v[114:115]
	v_pk_fma_f32 v[4:5], v[128:129], v[4:5], v[132:133]
	flat_store_dwordx4 v[142:143], v[2:5]
	flat_load_dwordx4 v[126:129], v[138:139] offset:64
	flat_load_dwordx4 v[130:133], v[140:141] offset:64
	v_mfma_f32_16x16x32_bf16 v[2:5], v[168:171], v[158:161], v[10:13]
	v_mfma_f32_16x16x32_bf16 v[62:65], v[164:167], v[146:149], v[62:65]
	s_waitcnt vmcnt(0) lgkmcnt(0)
	s_nop 0
	v_pk_fma_f32 v[10:11], v[122:123], v[126:127], v[130:131]
	v_pk_fma_f32 v[12:13], v[124:125], v[128:129], v[132:133]
	flat_store_dwordx4 v[142:143], v[10:13] offset:64
	flat_load_dwordx4 v[10:13], v[138:139] offset:128
	s_nop 0
	flat_load_dwordx4 v[122:125], v[140:141] offset:128
	v_mfma_f32_16x16x32_bf16 v[58:61], v[168:171], v[146:149], v[58:61]
	s_waitcnt vmcnt(0) lgkmcnt(0)
	v_pk_fma_f32 v[10:11], v[180:181], v[10:11], v[122:123]
	v_pk_fma_f32 v[12:13], v[182:183], v[12:13], v[124:125]
	flat_store_dwordx4 v[142:143], v[10:13] offset:128
	flat_load_dwordx4 v[122:125], v[138:139] offset:192
	flat_load_dwordx4 v[126:129], v[140:141] offset:192
	v_mfma_f32_16x16x32_bf16 v[54:57], v[172:175], v[146:149], v[54:57]
	s_waitcnt vmcnt(0) lgkmcnt(0)
	v_pk_fma_f32 v[122:123], v[184:185], v[122:123], v[126:127]
	v_pk_fma_f32 v[124:125], v[186:187], v[124:125], v[128:129]
	v_mfma_f32_16x16x32_bf16 v[50:53], v[176:179], v[146:149], v[50:53]
	flat_store_dwordx4 v[142:143], v[122:125] offset:192
	v_mfma_f32_16x16x32_bf16 v[46:49], v[164:167], v[150:153], v[46:49]
	v_mfma_f32_16x16x32_bf16 v[42:45], v[168:171], v[150:153], v[42:45]
	v_mfma_f32_16x16x32_bf16 v[38:41], v[172:175], v[150:153], v[38:41]
	v_mfma_f32_16x16x32_bf16 v[34:37], v[176:179], v[150:153], v[34:37]
	v_mfma_f32_16x16x32_bf16 v[30:33], v[164:167], v[154:157], v[30:33]
	v_mfma_f32_16x16x32_bf16 v[26:29], v[168:171], v[154:157], v[26:29]
	v_mfma_f32_16x16x32_bf16 v[22:25], v[172:175], v[154:157], v[22:25]
	v_mfma_f32_16x16x32_bf16 v[18:21], v[176:179], v[154:157], v[18:21]
	v_mfma_f32_16x16x32_bf16 v[14:17], v[164:167], v[158:161], v[14:17]
	v_mfma_f32_16x16x32_bf16 v[6:9], v[172:175], v[158:161], v[6:9]
	v_mfma_f32_16x16x32_bf16 v[10:13], v[176:179], v[158:161], v[134:137]
	v_add_u32_e32 v122, 16, v116
	v_min_i32_e32 v0, 0x8000, v122
	v_cmp_gt_i32_e32 vcc, s58, v122
	v_ashrrev_i32_e32 v117, 12, v0
	v_add_u32_e32 v0, 0xffff8010, v116
	v_ashrrev_i32_e32 v123, 31, v122
	v_cndmask_b32_e32 v125, 0, v123, vcc
	v_cndmask_b32_e32 v124, v0, v122, vcc
	v_cndmask_b32_e32 v127, v118, v119, vcc
	v_cndmask_b32_e32 v126, v120, v121, vcc
	v_lshlrev_b64 v[124:125], 12, v[124:125]
	v_lshl_add_u64 v[124:125], v[126:127], 0, v[124:125]
	v_lshlrev_b64 v[122:123], 12, v[122:123]
	v_lshlrev_b64 v[126:127], 12, v[0:1]
	v_lshl_add_u64 v[122:123], s[48:49], 0, v[122:123]
	v_lshl_add_u64 v[126:127], s[94:95], 0, v[126:127]
	v_cndmask_b32_e32 v123, v127, v123, vcc
	v_cndmask_b32_e32 v122, v126, v122, vcc
	v_mul_hi_i32_i24_e32 v127, 0x6000, v117
	v_mul_i32_i24_e32 v126, 0x6000, v117
	v_lshl_add_u64 v[126:127], s[4:5], 0, v[126:127]
	v_lshl_add_u64 v[130:131], v[126:127], 0, v[114:115]
	v_lshl_add_u64 v[132:133], v[124:125], 0, v[114:115]
	v_lshl_add_u64 v[134:135], v[122:123], 0, v[114:115]
	global_load_dwordx4 v[156:159], v[130:131], off
	global_load_dwordx4 v[164:167], v[130:131], off offset:64
	global_load_dwordx4 v[168:171], v[130:131], off offset:128
	global_load_dwordx4 v[172:175], v[130:131], off offset:192
	global_load_dwordx4 v[140:143], v[132:133], off
	global_load_dwordx4 v[144:147], v[132:133], off offset:64
	global_load_dwordx4 v[148:151], v[132:133], off offset:128
	global_load_dwordx4 v[152:155], v[132:133], off offset:192
	v_mov_b32_e32 v216, 0x10000
	v_mov_b32_e32 v217, 0
	v_lshl_add_u64 v[212:213], v[132:133], 0, v[216:217]
	v_lshl_add_u64 v[214:215], v[134:135], 0, v[216:217]
	global_load_dwordx4 v[176:179], v[212:213], off
	global_load_dwordx4 v[180:183], v[212:213], off offset:64
	global_load_dwordx4 v[184:187], v[212:213], off offset:128
	global_load_dwordx4 v[188:191], v[212:213], off offset:192
	v_lshl_add_u64 v[212:213], v[212:213], 0, v[216:217]
	s_waitcnt vmcnt(4)
; #define LAUNDER_IDS const int tid__ = launder_v((int)threadIdx.x); const int blk__ = launder_s((int)blockIdx.x); (void)tid__; (void)blk__;
; template <int MI, int NI>
; DI void resid_tile(const u16* A, int K, const u16* Bt, const float* gate, const float* xl_in, const float* xc_in, float* xl_out, float* xc_out,
;                    int m0, int n0, char* smem) {
;     ...
; #pragma unroll
;   for (int mi = 0; mi < MI; ++mi) {
;     const int m = m0 + wr * 16 * MI + mi * 16 + lr;
;     const int b9 = m < NTL ? m >> 12 : 8;
;     const float* xi = xrow(xl_in, xc_in, m);
;     float* xo = m < NTL ? xl_out + (size_t)m * D : xc_out + (size_t)(m - NTL) * D;
; #pragma unroll
;     for (int ni = 0; ni < NI; ++ni) {
;       const int n = n0 + wc * 16 * NI + ni * 16 + lq * 4;
;       const float4 g = *(const float4*)(gate + (size_t)b9 * 6144 + n);
;       const float4 xv = *(const float4*)(xi + n);
;       float4 ov;
;       ov.x = xv.x + g.x * acc[mi][ni][0]; ov.y = xv.y + g.y * acc[mi][ni][1]; ov.z = xv.z + g.z * acc[mi][ni][2]; ov.w = xv.w + g.w * acc[mi][ni][3];
;       *(float4*)(xo + n) = ov;
;     }
;     __builtin_amdgcn_sched_barrier(0);
;   }
;   EPI_END
; }
; DI void phase_resid(const Params& p, const u16* A, int K, const u16* Bt, const float* gate  ,
;                     const float* xl_in, const float* xc_in, float* xl_out, float* xc_out, int Mout, char* smem) {
;   LAUNDER_IDS
;   for (int it = 0;; ++it) {
;     int tm, tn;
;     if (!tile_map(it, NTL / 256, 8, blk__, gridDim.x, tm, tn)) break;
;     resid_tile<8, 4>(A, K, Bt, gate, xl_in, xc_in, xl_out, xc_out, tm * 256, tn * 128, smem);
;   }
	v_pk_fma_f32 v[110:111], v[110:111], v[156:157], v[140:141]
	v_pk_fma_f32 v[112:113], v[112:113], v[158:159], v[142:143]
	v_pk_fma_f32 v[106:107], v[106:107], v[164:165], v[144:145]
	v_pk_fma_f32 v[108:109], v[108:109], v[166:167], v[146:147]
	v_pk_fma_f32 v[102:103], v[102:103], v[168:169], v[148:149]
	v_pk_fma_f32 v[104:105], v[104:105], v[170:171], v[150:151]
	v_pk_fma_f32 v[98:99], v[98:99], v[172:173], v[152:153]
	v_pk_fma_f32 v[100:101], v[100:101], v[174:175], v[154:155]
	global_store_dwordx4 v[134:135], v[110:113], off
	global_store_dwordx4 v[134:135], v[106:109], off offset:64
	global_store_dwordx4 v[134:135], v[102:105], off offset:128
	global_store_dwordx4 v[134:135], v[98:101], off offset:192
	global_load_dwordx4 v[140:143], v[212:213], off
	global_load_dwordx4 v[144:147], v[212:213], off offset:64
	global_load_dwordx4 v[148:151], v[212:213], off offset:128
	global_load_dwordx4 v[152:155], v[212:213], off offset:192
	v_lshl_add_u64 v[212:213], v[212:213], 0, v[216:217]
	s_waitcnt vmcnt(8)
	v_pk_fma_f32 v[94:95], v[94:95], v[156:157], v[176:177]
	v_pk_fma_f32 v[96:97], v[96:97], v[158:159], v[178:179]
	v_pk_fma_f32 v[90:91], v[90:91], v[164:165], v[180:181]
	v_pk_fma_f32 v[92:93], v[92:93], v[166:167], v[182:183]
	v_pk_fma_f32 v[86:87], v[86:87], v[168:169], v[184:185]
	v_pk_fma_f32 v[88:89], v[88:89], v[170:171], v[186:187]
	v_pk_fma_f32 v[82:83], v[82:83], v[172:173], v[188:189]
	v_pk_fma_f32 v[84:85], v[84:85], v[174:175], v[190:191]
	global_store_dwordx4 v[214:215], v[94:97], off
	global_store_dwordx4 v[214:215], v[90:93], off offset:64
	global_store_dwordx4 v[214:215], v[86:89], off offset:128
	global_store_dwordx4 v[214:215], v[82:85], off offset:192
	v_lshl_add_u64 v[214:215], v[214:215], 0, v[216:217]
	global_load_dwordx4 v[176:179], v[212:213], off
	global_load_dwordx4 v[180:183], v[212:213], off offset:64
	global_load_dwordx4 v[184:187], v[212:213], off offset:128
	global_load_dwordx4 v[188:191], v[212:213], off offset:192
	v_lshl_add_u64 v[212:213], v[212:213], 0, v[216:217]
	s_waitcnt vmcnt(8)
	v_pk_fma_f32 v[74:75], v[74:75], v[156:157], v[140:141]
	v_pk_fma_f32 v[76:77], v[76:77], v[158:159], v[142:143]
	v_pk_fma_f32 v[78:79], v[78:79], v[164:165], v[144:145]
	v_pk_fma_f32 v[80:81], v[80:81], v[166:167], v[146:147]
	v_pk_fma_f32 v[70:71], v[70:71], v[168:169], v[148:149]
	v_pk_fma_f32 v[72:73], v[72:73], v[170:171], v[150:151]
	v_pk_fma_f32 v[66:67], v[66:67], v[172:173], v[152:153]
	v_pk_fma_f32 v[68:69], v[68:69], v[174:175], v[154:155]
	global_store_dwordx4 v[214:215], v[74:77], off
	global_store_dwordx4 v[214:215], v[78:81], off offset:64
	global_store_dwordx4 v[214:215], v[70:73], off offset:128
	global_store_dwordx4 v[214:215], v[66:69], off offset:192
	v_lshl_add_u64 v[214:215], v[214:215], 0, v[216:217]
	global_load_dwordx4 v[140:143], v[212:213], off
	global_load_dwordx4 v[144:147], v[212:213], off offset:64
	global_load_dwordx4 v[148:151], v[212:213], off offset:128
	global_load_dwordx4 v[152:155], v[212:213], off offset:192
	v_lshl_add_u64 v[212:213], v[212:213], 0, v[216:217]
	s_waitcnt vmcnt(8)
	v_pk_fma_f32 v[62:63], v[62:63], v[156:157], v[176:177]
	v_pk_fma_f32 v[64:65], v[64:65], v[158:159], v[178:179]
	v_pk_fma_f32 v[58:59], v[58:59], v[164:165], v[180:181]
	v_pk_fma_f32 v[60:61], v[60:61], v[166:167], v[182:183]
	v_pk_fma_f32 v[54:55], v[54:55], v[168:169], v[184:185]
	v_pk_fma_f32 v[56:57], v[56:57], v[170:171], v[186:187]
	v_pk_fma_f32 v[50:51], v[50:51], v[172:173], v[188:189]
	v_pk_fma_f32 v[52:53], v[52:53], v[174:175], v[190:191]
	global_store_dwordx4 v[214:215], v[62:65], off
	global_store_dwordx4 v[214:215], v[58:61], off offset:64
	global_store_dwordx4 v[214:215], v[54:57], off offset:128
	global_store_dwordx4 v[214:215], v[50:53], off offset:192
	v_lshl_add_u64 v[214:215], v[214:215], 0, v[216:217]
	global_load_dwordx4 v[176:179], v[212:213], off
	global_load_dwordx4 v[180:183], v[212:213], off offset:64
	global_load_dwordx4 v[184:187], v[212:213], off offset:128
	global_load_dwordx4 v[188:191], v[212:213], off offset:192
	v_lshl_add_u64 v[212:213], v[212:213], 0, v[216:217]
	s_waitcnt vmcnt(8)
	v_pk_fma_f32 v[46:47], v[46:47], v[156:157], v[140:141]
	v_pk_fma_f32 v[48:49], v[48:49], v[158:159], v[142:143]
	v_pk_fma_f32 v[42:43], v[42:43], v[164:165], v[144:145]
	v_pk_fma_f32 v[44:45], v[44:45], v[166:167], v[146:147]
	v_pk_fma_f32 v[38:39], v[38:39], v[168:169], v[148:149]
	v_pk_fma_f32 v[40:41], v[40:41], v[170:171], v[150:151]
	v_pk_fma_f32 v[34:35], v[34:35], v[172:173], v[152:153]
	v_pk_fma_f32 v[36:37], v[36:37], v[174:175], v[154:155]
	global_store_dwordx4 v[214:215], v[46:49], off
	global_store_dwordx4 v[214:215], v[42:45], off offset:64
	global_store_dwordx4 v[214:215], v[38:41], off offset:128
	global_store_dwordx4 v[214:215], v[34:37], off offset:192
	v_lshl_add_u64 v[214:215], v[214:215], 0, v[216:217]
	global_load_dwordx4 v[140:143], v[212:213], off
	global_load_dwordx4 v[144:147], v[212:213], off offset:64
	global_load_dwordx4 v[148:151], v[212:213], off offset:128
	global_load_dwordx4 v[152:155], v[212:213], off offset:192
	s_waitcnt vmcnt(8)
	v_pk_fma_f32 v[30:31], v[30:31], v[156:157], v[176:177]
	v_pk_fma_f32 v[32:33], v[32:33], v[158:159], v[178:179]
	v_pk_fma_f32 v[26:27], v[26:27], v[164:165], v[180:181]
	v_pk_fma_f32 v[28:29], v[28:29], v[166:167], v[182:183]
	v_pk_fma_f32 v[22:23], v[22:23], v[168:169], v[184:185]
	v_pk_fma_f32 v[24:25], v[24:25], v[170:171], v[186:187]
	v_pk_fma_f32 v[18:19], v[18:19], v[172:173], v[188:189]
	v_pk_fma_f32 v[20:21], v[20:21], v[174:175], v[190:191]
	global_store_dwordx4 v[214:215], v[30:33], off
	global_store_dwordx4 v[214:215], v[26:29], off offset:64
	global_store_dwordx4 v[214:215], v[22:25], off offset:128
	global_store_dwordx4 v[214:215], v[18:21], off offset:192
	v_lshl_add_u64 v[214:215], v[214:215], 0, v[216:217]
	s_waitcnt vmcnt(4)
	v_pk_fma_f32 v[14:15], v[14:15], v[156:157], v[140:141]
	v_pk_fma_f32 v[16:17], v[16:17], v[158:159], v[142:143]
	v_pk_fma_f32 v[2:3], v[2:3], v[164:165], v[144:145]
	v_pk_fma_f32 v[4:5], v[4:5], v[166:167], v[146:147]
	v_pk_fma_f32 v[6:7], v[6:7], v[168:169], v[148:149]
	v_pk_fma_f32 v[8:9], v[8:9], v[170:171], v[150:151]
	v_pk_fma_f32 v[10:11], v[10:11], v[172:173], v[152:153]
	v_pk_fma_f32 v[12:13], v[12:13], v[174:175], v[154:155]
	global_store_dwordx4 v[214:215], v[14:17], off
	global_store_dwordx4 v[214:215], v[2:5], off offset:64
	global_store_dwordx4 v[214:215], v[6:9], off offset:128
	global_store_dwordx4 v[214:215], v[10:13], off offset:192
	s_add_i32 s9, s9, 1
	s_mul_i32 s4, s9, s39
	s_add_i32 s4, s4, s7
	s_cmpk_gt_i32 s4, 0x7f
	s_cbranch_scc0 .LBB0_461

; template <int MI, int NI>
; DI void gemm256(f32x4 (&acc)[MI][NI], const u16* __restrict__ A, int lda, const u16* __restrict__ Bt, int ldb, int K, int m0, int n0, char* smem) {
;     ...
;   for (int kt = 0; kt < nk; ++kt) {
;     if (kt + 1 < nk) asm volatile("s_waitcnt vmcnt(%0) lgkmcnt(0)" :: "n"(LPS) : "memory");
;     else asm volatile("s_waitcnt vmcnt(0) lgkmcnt(0)" ::: "memory");
;     __builtin_amdgcn_s_barrier();
;     __builtin_amdgcn_s_setprio(1);
;     const char* sb = smem + st * STAGE + foff;
;     bf16x8 af[MI], bfr[NI];
; #pragma unroll
;     for (int mi = 0; mi < MI; ++mi) af[mi] = *(const bf16x8*)(sb + (wr * MI + mi) * 1024);
; #pragma unroll
;     for (int ni = 0; ni < NI; ++ni) bfr[ni] = *(const bf16x8*)(sb + ABYTES + (wc * NI + ni) * 1024);
;     __builtin_amdgcn_sched_barrier(0x0);
;     if (kt + 2 < nk) { const int s2 = st >= 1 ? st - 1 : 2; G256_ISSUE(s2, (kt + 2) * 32); }
;     __builtin_amdgcn_s_setprio(0);
; #pragma unroll
;     for (int mi = 0; mi < MI; ++mi)
; #pragma unroll
;       for (int ni = 0; ni < NI; ++ni)
;         acc[mi][ni] = __builtin_amdgcn_mfma_f32_16x16x32_bf16(bfr[ni], af[mi], acc[mi][ni], 0, 0, 0);
;     st = st == 2 ? 0 : st + 1;
;   }
.Lpipe_zgemm:
	v_add_u32_e32 v160, s6, v143
	ds_read_b128 v[164:167], v160 offset:4096
	ds_read_b128 v[168:171], v160 offset:5120
	ds_read_b128 v[172:175], v160 offset:6144
	ds_read_b128 v[176:179], v160 offset:7168
	s_add_i32 s8, s6, 0xffffa000
	s_cmp_eq_u32 s6, 0
	s_cselect_b32 s8, 0xc000, s8
	s_add_i32 s9, s8, s7
	s_add_i32 s8, s8, s0
	s_mov_b32 m0, s9
	s_waitcnt lgkmcnt(7)
	v_mfma_f32_16x16x32_bf16 v[126:129], v[180:183], v[144:147], v[126:129]
	global_load_lds_dwordx4 v[198:199], off
	v_mfma_f32_16x16x32_bf16 v[110:113], v[180:183], v[148:151], v[110:113]
	v_lshl_add_u64 v[198:199], v[198:199], 0, s[98:99]
	s_add_i32 m0, s9, 0x400
	v_mfma_f32_16x16x32_bf16 v[94:97], v[180:183], v[152:155], v[94:97]
	global_load_lds_dwordx4 v[200:201], off
	v_mfma_f32_16x16x32_bf16 v[78:81], v[180:183], v[156:159], v[78:81]
	v_lshl_add_u64 v[200:201], v[200:201], 0, s[98:99]
	s_add_i32 m0, s9, 0x800
	s_waitcnt lgkmcnt(6)
	v_mfma_f32_16x16x32_bf16 v[122:125], v[184:187], v[144:147], v[122:125]
	global_load_lds_dwordx4 v[202:203], off
	v_mfma_f32_16x16x32_bf16 v[106:109], v[184:187], v[148:151], v[106:109]
	v_lshl_add_u64 v[202:203], v[202:203], 0, s[98:99]
	s_add_i32 m0, s9, 0xc00
	v_mfma_f32_16x16x32_bf16 v[90:93], v[184:187], v[152:155], v[90:93]
	global_load_lds_dwordx4 v[204:205], off
	v_mfma_f32_16x16x32_bf16 v[74:77], v[184:187], v[156:159], v[74:77]
	v_lshl_add_u64 v[204:205], v[204:205], 0, s[98:99]
	s_mov_b32 m0, s8
	s_waitcnt lgkmcnt(5)
	v_mfma_f32_16x16x32_bf16 v[118:121], v[188:191], v[144:147], v[118:121]
	global_load_lds_dwordx4 v[206:207], off
	v_mfma_f32_16x16x32_bf16 v[102:105], v[188:191], v[148:151], v[102:105]
	v_lshl_add_u64 v[206:207], v[206:207], 0, s[98:99]
	s_add_i32 m0, s8, 0x400
	v_mfma_f32_16x16x32_bf16 v[86:89], v[188:191], v[152:155], v[86:89]
	global_load_lds_dwordx4 v[208:209], off
	v_mfma_f32_16x16x32_bf16 v[70:73], v[188:191], v[156:159], v[70:73]
	v_lshl_add_u64 v[208:209], v[208:209], 0, s[98:99]
	s_waitcnt lgkmcnt(4)
	v_mfma_f32_16x16x32_bf16 v[114:117], v[192:195], v[144:147], v[114:117]
	s_add_i32 s9, s6, 0x6000
	v_mfma_f32_16x16x32_bf16 v[98:101], v[192:195], v[148:151], v[98:101]
	s_cmp_eq_u32 s6, 0xc000
	s_cselect_b32 s6, 0, s9
	v_mfma_f32_16x16x32_bf16 v[82:85], v[192:195], v[152:155], v[82:85]
	v_add_u32_e32 v196, s6, v143
	v_mfma_f32_16x16x32_bf16 v[66:69], v[192:195], v[156:159], v[66:69]
	v_add_u32_e32 v197, s6, v0
	s_waitcnt vmcnt(6) lgkmcnt(0)
	s_barrier
	v_mfma_f32_16x16x32_bf16 v[62:65], v[180:183], v[164:167], v[62:65]
	ds_read_b128 v[144:147], v196
	v_mfma_f32_16x16x32_bf16 v[46:49], v[180:183], v[168:171], v[46:49]
	ds_read_b128 v[148:151], v196 offset:1024
	v_mfma_f32_16x16x32_bf16 v[30:33], v[180:183], v[172:175], v[30:33]
	ds_read_b128 v[152:155], v196 offset:2048
	v_mfma_f32_16x16x32_bf16 v[14:17], v[180:183], v[176:179], v[14:17]
	ds_read_b128 v[156:159], v196 offset:3072
	ds_read_b128 v[180:183], v197 offset:16384
	v_mfma_f32_16x16x32_bf16 v[58:61], v[184:187], v[164:167], v[58:61]
	v_mfma_f32_16x16x32_bf16 v[42:45], v[184:187], v[168:171], v[42:45]
	v_mfma_f32_16x16x32_bf16 v[26:29], v[184:187], v[172:175], v[26:29]
	v_mfma_f32_16x16x32_bf16 v[10:13], v[184:187], v[176:179], v[10:13]
	ds_read_b128 v[184:187], v197 offset:17408
	v_mfma_f32_16x16x32_bf16 v[54:57], v[188:191], v[164:167], v[54:57]
	v_mfma_f32_16x16x32_bf16 v[38:41], v[188:191], v[168:171], v[38:41]
	v_mfma_f32_16x16x32_bf16 v[22:25], v[188:191], v[172:175], v[22:25]
	v_mfma_f32_16x16x32_bf16 v[6:9], v[188:191], v[176:179], v[6:9]
	ds_read_b128 v[188:191], v197 offset:18432
	v_mfma_f32_16x16x32_bf16 v[50:53], v[192:195], v[164:167], v[50:53]
	v_mfma_f32_16x16x32_bf16 v[34:37], v[192:195], v[168:171], v[34:37]
	v_mfma_f32_16x16x32_bf16 v[18:21], v[192:195], v[172:175], v[18:21]
	v_mfma_f32_16x16x32_bf16 v[2:5], v[192:195], v[176:179], v[2:5]
	ds_read_b128 v[192:195], v197 offset:19456
	s_sub_i32 s1, s1, 1
	s_cmp_lg_u32 s1, 0
	s_cbranch_scc1 .Lpipe_zgemm
	v_add_u32_e32 v160, s6, v143
	ds_read_b128 v[164:167], v160 offset:4096
	ds_read_b128 v[168:171], v160 offset:5120
	ds_read_b128 v[172:175], v160 offset:6144
	ds_read_b128 v[176:179], v160 offset:7168
	s_add_i32 s8, s6, 0xffffa000
	s_cmp_eq_u32 s6, 0
	s_cselect_b32 s8, 0xc000, s8
	s_add_i32 s9, s8, s7
	s_add_i32 s8, s8, s0
	s_mov_b32 m0, s9
	s_waitcnt lgkmcnt(7)
	v_mfma_f32_16x16x32_bf16 v[126:129], v[180:183], v[144:147], v[126:129]
	global_load_lds_dwordx4 v[198:199], off
	v_mfma_f32_16x16x32_bf16 v[110:113], v[180:183], v[148:151], v[110:113]
	v_lshl_add_u64 v[198:199], v[198:199], 0, s[98:99]
	s_add_i32 m0, s9, 0x400
	v_mfma_f32_16x16x32_bf16 v[94:97], v[180:183], v[152:155], v[94:97]
	global_load_lds_dwordx4 v[200:201], off
	v_mfma_f32_16x16x32_bf16 v[78:81], v[180:183], v[156:159], v[78:81]
	v_lshl_add_u64 v[200:201], v[200:201], 0, s[98:99]
	s_add_i32 m0, s9, 0x800
	s_waitcnt lgkmcnt(6)
	v_mfma_f32_16x16x32_bf16 v[122:125], v[184:187], v[144:147], v[122:125]
	global_load_lds_dwordx4 v[202:203], off
	v_mfma_f32_16x16x32_bf16 v[106:109], v[184:187], v[148:151], v[106:109]
	v_lshl_add_u64 v[202:203], v[202:203], 0, s[98:99]
	s_add_i32 m0, s9, 0xc00
	v_mfma_f32_16x16x32_bf16 v[90:93], v[184:187], v[152:155], v[90:93]
	global_load_lds_dwordx4 v[204:205], off
	v_mfma_f32_16x16x32_bf16 v[74:77], v[184:187], v[156:159], v[74:77]
	v_lshl_add_u64 v[204:205], v[204:205], 0, s[98:99]
	s_mov_b32 m0, s8
	s_waitcnt lgkmcnt(5)
	v_mfma_f32_16x16x32_bf16 v[118:121], v[188:191], v[144:147], v[118:121]
	global_load_lds_dwordx4 v[206:207], off
	v_mfma_f32_16x16x32_bf16 v[102:105], v[188:191], v[148:151], v[102:105]
	v_lshl_add_u64 v[206:207], v[206:207], 0, s[98:99]
	s_add_i32 m0, s8, 0x400
	v_mfma_f32_16x16x32_bf16 v[86:89], v[188:191], v[152:155], v[86:89]
	global_load_lds_dwordx4 v[208:209], off
	v_mfma_f32_16x16x32_bf16 v[70:73], v[188:191], v[156:159], v[70:73]
	v_lshl_add_u64 v[208:209], v[208:209], 0, s[98:99]
	s_waitcnt lgkmcnt(4)
; template <int MI, int NI>
; DI void gemm256(f32x4 (&acc)[MI][NI], const u16* __restrict__ A, int lda, const u16* __restrict__ Bt, int ldb, int K, int m0, int n0, char* smem) {
;     ...
;   for (int kt = 0; kt < nk; ++kt) {
;     if (kt + 1 < nk) asm volatile("s_waitcnt vmcnt(%0) lgkmcnt(0)" :: "n"(LPS) : "memory");
;     else asm volatile("s_waitcnt vmcnt(0) lgkmcnt(0)" ::: "memory");
;     __builtin_amdgcn_s_barrier();
;     __builtin_amdgcn_s_setprio(1);
;     const char* sb = smem + st * STAGE + foff;
;     bf16x8 af[MI], bfr[NI];
; #pragma unroll
;     for (int mi = 0; mi < MI; ++mi) af[mi] = *(const bf16x8*)(sb + (wr * MI + mi) * 1024);
; #pragma unroll
;     for (int ni = 0; ni < NI; ++ni) bfr[ni] = *(const bf16x8*)(sb + ABYTES + (wc * NI + ni) * 1024);
;     __builtin_amdgcn_sched_barrier(0x0);
;     if (kt + 2 < nk) { const int s2 = st >= 1 ? st - 1 : 2; G256_ISSUE(s2, (kt + 2) * 32); }
;     __builtin_amdgcn_s_setprio(0);
; #pragma unroll
;     for (int mi = 0; mi < MI; ++mi)
; #pragma unroll
;       for (int ni = 0; ni < NI; ++ni)
;         acc[mi][ni] = __builtin_amdgcn_mfma_f32_16x16x32_bf16(bfr[ni], af[mi], acc[mi][ni], 0, 0, 0);
;     st = st == 2 ? 0 : st + 1;
;   }
;   asm volatile("s_waitcnt lgkmcnt(0)" ::: "memory");
;   __builtin_amdgcn_s_barrier();
	v_mfma_f32_16x16x32_bf16 v[114:117], v[192:195], v[144:147], v[114:117]
	v_mfma_f32_16x16x32_bf16 v[98:101], v[192:195], v[148:151], v[98:101]
	v_mfma_f32_16x16x32_bf16 v[82:85], v[192:195], v[152:155], v[82:85]
	v_mfma_f32_16x16x32_bf16 v[66:69], v[192:195], v[156:159], v[66:69]
	s_waitcnt lgkmcnt(0)
	v_mfma_f32_16x16x32_bf16 v[62:65], v[180:183], v[164:167], v[62:65]
	v_mfma_f32_16x16x32_bf16 v[46:49], v[180:183], v[168:171], v[46:49]
	v_mfma_f32_16x16x32_bf16 v[30:33], v[180:183], v[172:175], v[30:33]
	v_mfma_f32_16x16x32_bf16 v[14:17], v[180:183], v[176:179], v[14:17]
	v_mfma_f32_16x16x32_bf16 v[58:61], v[184:187], v[164:167], v[58:61]
	v_mfma_f32_16x16x32_bf16 v[42:45], v[184:187], v[168:171], v[42:45]
	v_mfma_f32_16x16x32_bf16 v[26:29], v[184:187], v[172:175], v[26:29]
	v_mfma_f32_16x16x32_bf16 v[10:13], v[184:187], v[176:179], v[10:13]
	v_mfma_f32_16x16x32_bf16 v[54:57], v[188:191], v[164:167], v[54:57]
	v_mfma_f32_16x16x32_bf16 v[38:41], v[188:191], v[168:171], v[38:41]
	v_mfma_f32_16x16x32_bf16 v[22:25], v[188:191], v[172:175], v[22:25]
	v_mfma_f32_16x16x32_bf16 v[6:9], v[188:191], v[176:179], v[6:9]
	v_mfma_f32_16x16x32_bf16 v[50:53], v[192:195], v[164:167], v[50:53]
	v_mfma_f32_16x16x32_bf16 v[34:37], v[192:195], v[168:171], v[34:37]
	v_mfma_f32_16x16x32_bf16 v[18:21], v[192:195], v[172:175], v[18:21]
	v_mfma_f32_16x16x32_bf16 v[2:5], v[192:195], v[176:179], v[2:5]
	s_waitcnt vmcnt(6) lgkmcnt(0)
	s_barrier
	s_setprio 1
	v_add_u32_e32 v0, v140, v142
	ds_read_b128 v[130:133], v0
	ds_read_b128 v[142:145], v0 offset:1024
	ds_read_b128 v[146:149], v0 offset:2048
	ds_read_b128 v[150:153], v0 offset:3072
	ds_read_b128 v[154:157], v0 offset:4096
	ds_read_b128 v[158:161], v0 offset:5120
	ds_read_b128 v[164:167], v0 offset:6144
	ds_read_b128 v[168:171], v0 offset:7168
	v_add_u32_e32 v220, v140, v141
	ds_read_b128 v[138:141], v220 offset:16384
	ds_read_b128 v[172:175], v220 offset:17408
	ds_read_b128 v[176:179], v220 offset:18432
	ds_read_b128 v[180:183], v220 offset:19456
	s_setprio 0
	s_waitcnt lgkmcnt(3)
	v_mfma_f32_16x16x32_bf16 v[126:129], v[138:141], v[130:133], v[126:129]
	s_waitcnt vmcnt(0) lgkmcnt(0)
	s_barrier
	s_waitcnt lgkmcnt(2)
	v_mfma_f32_16x16x32_bf16 v[122:125], v[172:175], v[130:133], v[122:125]
	s_waitcnt lgkmcnt(1)
	v_mfma_f32_16x16x32_bf16 v[118:121], v[176:179], v[130:133], v[118:121]
	s_waitcnt lgkmcnt(0)
	v_mfma_f32_16x16x32_bf16 v[130:133], v[180:183], v[130:133], v[114:117]
	v_mfma_f32_16x16x32_bf16 v[110:113], v[138:141], v[142:145], v[110:113]
	v_mfma_f32_16x16x32_bf16 v[102:105], v[176:179], v[142:145], v[102:105]
	v_mfma_f32_16x16x32_bf16 v[94:97], v[138:141], v[146:149], v[94:97]
	v_mfma_f32_16x16x32_bf16 v[86:89], v[176:179], v[146:149], v[86:89]
	v_mfma_f32_16x16x32_bf16 v[78:81], v[138:141], v[150:153], v[78:81]
	v_mfma_f32_16x16x32_bf16 v[70:73], v[176:179], v[150:153], v[70:73]
	v_mfma_f32_16x16x32_bf16 v[62:65], v[138:141], v[154:157], v[62:65]
	v_mfma_f32_16x16x32_bf16 v[54:57], v[176:179], v[154:157], v[54:57]
	v_mfma_f32_16x16x32_bf16 v[46:49], v[138:141], v[158:161], v[46:49]
	v_mfma_f32_16x16x32_bf16 v[38:41], v[176:179], v[158:161], v[38:41]
	v_mfma_f32_16x16x32_bf16 v[30:33], v[138:141], v[164:167], v[30:33]
	v_mfma_f32_16x16x32_bf16 v[22:25], v[176:179], v[164:167], v[22:25]
	v_mfma_f32_16x16x32_bf16 v[14:17], v[138:141], v[168:171], v[14:17]
	v_mfma_f32_16x16x32_bf16 v[6:9], v[176:179], v[168:171], v[6:9]
	v_mfma_f32_16x16x32_bf16 v[184:187], v[172:175], v[142:145], v[106:109]
	v_mfma_f32_16x16x32_bf16 v[142:145], v[180:183], v[142:145], v[98:101]
	v_mfma_f32_16x16x32_bf16 v[188:191], v[172:175], v[146:149], v[90:93]
	v_mfma_f32_16x16x32_bf16 v[146:149], v[180:183], v[146:149], v[82:85]
	v_mfma_f32_16x16x32_bf16 v[192:195], v[172:175], v[150:153], v[74:77]
	v_mfma_f32_16x16x32_bf16 v[150:153], v[180:183], v[150:153], v[66:69]
	v_mfma_f32_16x16x32_bf16 v[196:199], v[172:175], v[154:157], v[58:61]
	v_mfma_f32_16x16x32_bf16 v[154:157], v[180:183], v[154:157], v[50:53]
	v_mfma_f32_16x16x32_bf16 v[200:203], v[172:175], v[158:161], v[42:45]
	v_mfma_f32_16x16x32_bf16 v[158:161], v[180:183], v[158:161], v[34:37]
	v_mfma_f32_16x16x32_bf16 v[204:207], v[172:175], v[164:167], v[26:29]
	v_mfma_f32_16x16x32_bf16 v[164:167], v[180:183], v[164:167], v[18:21]
	v_mfma_f32_16x16x32_bf16 v[138:141], v[172:175], v[168:171], v[10:13]
	v_mfma_f32_16x16x32_bf16 v[168:171], v[180:183], v[168:171], v[2:5]
	s_setprio 1
	s_nop 1
	ds_read_b128 v[2:5], v0 offset:24576
	ds_read_b128 v[10:13], v0 offset:25600
	ds_read_b128 v[18:21], v0 offset:26624
	ds_read_b128 v[26:29], v0 offset:27648
	ds_read_b128 v[34:37], v0 offset:28672
	ds_read_b128 v[172:175], v0 offset:29696
	ds_read_b128 v[176:179], v0 offset:30720
	ds_read_b128 v[180:183], v0 offset:31744
	ds_read_b128 v[208:211], v220 offset:40960
	ds_read_b128 v[212:215], v220 offset:41984
	ds_read_b128 v[216:219], v220 offset:43008
	ds_read_b128 v[220:223], v220 offset:44032
	s_setprio 0
	s_waitcnt lgkmcnt(3)
	v_mfma_f32_16x16x32_bf16 v[224:227], v[208:211], v[2:5], v[126:129]
	v_mov_b32_e32 v0, v136
	s_waitcnt lgkmcnt(0)
	s_barrier
; DI unsigned pack2(float a, float b) { float2_t v = {a, b}; bf16x2_t r = __builtin_convertvector(v, bf16x2_t); return __builtin_bit_cast(unsigned, r); }
; #define EPI_BEGIN const int lr1_ = launder_v(lr), lq1_ = launder_v(lq), wr1_ = launder_v(wr), wc1_ = launder_v(wc); { const int lr = lr1_, lq = lq1_, wr = wr1_, wc = wc1_; (void)lr; (void)lq; (void)wr; (void)wc;
; DI void phase_zgemm(const Params& p, int l, char* smem) {
;     ...
;     EPI_BEGIN
; #pragma unroll
;     for (int mi = 0; mi < 8; mi += 2) {
;       const int m = m0 + wr * 128 + (mi + (lq & 1)) * 16 + lr;
; #pragma unroll
;       for (int ni = 0; ni < 4; ++ni) {
;         const int n = n0 + wc * 64 + ni * 16 + (lq >> 1) * 8;
;         const uint4 v = widen16(make_uint2(pack2(acc[mi][ni][0], acc[mi][ni][1]), pack2(acc[mi][ni][2], acc[mi][ni][3])),
;                                 make_uint2(pack2(acc[mi + 1][ni][0], acc[mi + 1][ni][1]), pack2(acc[mi + 1][ni][2], acc[mi + 1][ni][3])));
;         if (n < ZA) *(uint4*)(za + (size_t)m * ZA + n) = v;
;         else if (n < ZA + ZR) *(uint4*)(zr + (size_t)m * ZR + (n - ZA)) = v;
;       }
;     }
;     EPI_END
	s_waitcnt lgkmcnt(2)
	v_mfma_f32_16x16x32_bf16 v[114:117], v[212:215], v[2:5], v[122:125]
	s_movk_i32 s0, 0x900
	s_waitcnt lgkmcnt(1)
	v_mfma_f32_16x16x32_bf16 v[106:109], v[216:219], v[2:5], v[118:121]
	s_nop 0
	v_cvt_pk_bf16_f32 v122, v224, v225
	v_cvt_pk_bf16_f32 v123, v226, v227
	s_waitcnt lgkmcnt(0)
	v_mfma_f32_16x16x32_bf16 v[98:101], v[220:223], v[2:5], v[130:133]
	v_mov_b32_e32 v2, v137
	v_mov_b32_e32 v3, v134
	v_mov_b32_e32 v4, v135
	v_lshlrev_b32_e32 v3, 7, v3
	v_add3_u32 v132, v0, s5, v3
	v_lshlrev_b32_e32 v3, 2, v2
	v_and_b32_e32 v3, -8, v3
	v_lshlrev_b32_e32 v0, 6, v4
	v_add3_u32 v126, v3, s4, v0
	v_lshlrev_b32_e32 v0, 4, v2
	v_mfma_f32_16x16x32_bf16 v[228:231], v[208:211], v[10:13], v[110:113]
	v_and_b32_e32 v133, 16, v0
	v_add_u32_e32 v0, v132, v133
	v_mfma_f32_16x16x32_bf16 v[118:121], v[212:215], v[10:13], v[184:187]
	v_mfma_f32_16x16x32_bf16 v[110:113], v[216:219], v[10:13], v[102:105]
	s_nop 3
	v_cvt_pk_bf16_f32 v124, v228, v229
	v_cvt_pk_bf16_f32 v125, v230, v231
	s_nop 0
	v_permlane16_swap_b32_e32 v122, v124
	v_mfma_f32_16x16x32_bf16 v[102:105], v[220:223], v[10:13], v[142:145]
	v_permlane16_swap_b32_e32 v123, v125
	v_mfma_f32_16x16x32_bf16 v[10:13], v[216:219], v[176:179], v[22:25]
	s_nop 2
	v_mov_b64_e32 v[22:23], s[62:63]
	v_mfma_f32_16x16x32_bf16 v[90:93], v[208:211], v[18:21], v[94:97]
	v_mad_i64_i32 v[128:129], s[0:1], v0, s0, v[22:23]
	s_movk_i32 s0, 0x39f
	v_mfma_f32_16x16x32_bf16 v[82:85], v[212:215], v[18:21], v[188:191]
	v_cmp_lt_i32_e64 s[0:1], s0, v126
	v_mfma_f32_16x16x32_bf16 v[74:77], v[216:219], v[18:21], v[86:89]
	v_mfma_f32_16x16x32_bf16 v[66:69], v[220:223], v[18:21], v[146:149]
	v_mfma_f32_16x16x32_bf16 v[94:97], v[208:211], v[26:29], v[78:81]
	v_mfma_f32_16x16x32_bf16 v[86:89], v[212:215], v[26:29], v[192:195]
	v_mfma_f32_16x16x32_bf16 v[78:81], v[216:219], v[26:29], v[70:73]
	v_mfma_f32_16x16x32_bf16 v[70:73], v[220:223], v[26:29], v[150:153]
	v_mfma_f32_16x16x32_bf16 v[58:61], v[208:211], v[34:37], v[62:65]
	v_mfma_f32_16x16x32_bf16 v[50:53], v[212:215], v[34:37], v[196:199]
	v_mfma_f32_16x16x32_bf16 v[42:45], v[216:219], v[34:37], v[54:57]
	v_mfma_f32_16x16x32_bf16 v[34:37], v[220:223], v[34:37], v[154:157]
	v_mfma_f32_16x16x32_bf16 v[62:65], v[208:211], v[172:175], v[46:49]
	v_mfma_f32_16x16x32_bf16 v[54:57], v[212:215], v[172:175], v[200:203]
	v_mfma_f32_16x16x32_bf16 v[46:49], v[216:219], v[172:175], v[38:41]
	v_mfma_f32_16x16x32_bf16 v[38:41], v[220:223], v[172:175], v[158:161]
	v_mfma_f32_16x16x32_bf16 v[26:29], v[208:211], v[176:179], v[30:33]
	v_mfma_f32_16x16x32_bf16 v[18:21], v[212:215], v[176:179], v[204:207]
	v_mfma_f32_16x16x32_bf16 v[2:5], v[220:223], v[176:179], v[164:167]
	v_mfma_f32_16x16x32_bf16 v[30:33], v[208:211], v[180:183], v[14:17]
	v_mfma_f32_16x16x32_bf16 v[22:25], v[212:215], v[180:183], v[138:141]
	v_mfma_f32_16x16x32_bf16 v[14:17], v[216:219], v[180:183], v[6:9]
	v_mfma_f32_16x16x32_bf16 v[6:9], v[220:223], v[180:183], v[168:171]
	s_and_saveexec_b64 s[4:5], s[0:1]
	s_xor_b64 s[4:5], exec, s[4:5]
	s_cbranch_execz .LBB0_862
	s_movk_i32 s6, 0x820
	v_cmp_gt_u32_e32 vcc, s6, v126
	s_and_saveexec_b64 s[6:7], vcc
	s_cbranch_execz .LBB0_861
	v_mov_b32_e32 v127, v1
	v_lshl_add_u64 v[130:131], v[126:127], 1, v[128:129]
	v_add_co_u32_e32 v130, vcc, 0x47e0000, v130
	s_nop 1
	v_addc_co_u32_e32 v131, vcc, 0, v131, vcc
	flat_store_dwordx4 v[130:131], v[122:125] offset:2240

; template <int MI, int NI>
; DI void gemm256(f32x4 (&acc)[MI][NI], const u16* __restrict__ A, int lda, const u16* __restrict__ Bt, int ldb, int K, int m0, int n0, char* smem) {
;     ...
;   for (int kt = 0; kt < nk; ++kt) {
;     if (kt + 1 < nk) asm volatile("s_waitcnt vmcnt(%0) lgkmcnt(0)" :: "n"(LPS) : "memory");
;     else asm volatile("s_waitcnt vmcnt(0) lgkmcnt(0)" ::: "memory");
;     __builtin_amdgcn_s_barrier();
;     __builtin_amdgcn_s_setprio(1);
;     const char* sb = smem + st * STAGE + foff;
;     bf16x8 af[MI], bfr[NI];
; #pragma unroll
;     for (int mi = 0; mi < MI; ++mi) af[mi] = *(const bf16x8*)(sb + (wr * MI + mi) * 1024);
; #pragma unroll
;     for (int ni = 0; ni < NI; ++ni) bfr[ni] = *(const bf16x8*)(sb + ABYTES + (wc * NI + ni) * 1024);
;     __builtin_amdgcn_sched_barrier(0x0);
;     if (kt + 2 < nk) { const int s2 = st >= 1 ? st - 1 : 2; G256_ISSUE(s2, (kt + 2) * 32); }
;     __builtin_amdgcn_s_setprio(0);
; #pragma unroll
;     for (int mi = 0; mi < MI; ++mi)
; #pragma unroll
;       for (int ni = 0; ni < NI; ++ni)
;         acc[mi][ni] = __builtin_amdgcn_mfma_f32_16x16x32_bf16(bfr[ni], af[mi], acc[mi][ni], 0, 0, 0);
;     st = st == 2 ? 0 : st + 1;
;   }
.Lpipe_mlp2:
	v_add_u32_e32 v161, s11, v160
	ds_read_b128 v[156:159], v161 offset:4096
	ds_read_b128 v[164:167], v161 offset:5120
	ds_read_b128 v[168:171], v161 offset:6144
	ds_read_b128 v[172:175], v161 offset:7168
	s_add_i32 s12, s11, 0xffffa000
	s_cmp_eq_u32 s11, 0
	s_cselect_b32 s12, 0xc000, s12
	s_add_i32 s13, s12, s0
	s_add_i32 s12, s12, s1
	s_mov_b32 m0, s13
	s_waitcnt lgkmcnt(7)
	v_mfma_f32_16x16x32_bf16 v[126:129], v[176:179], v[140:143], v[126:129]
	global_load_lds_dwordx4 v[196:197], off
	v_mfma_f32_16x16x32_bf16 v[110:113], v[176:179], v[144:147], v[110:113]
	v_lshl_add_u64 v[196:197], v[196:197], 0, s[98:99]
	s_add_i32 m0, s13, 0x400
	v_mfma_f32_16x16x32_bf16 v[94:97], v[176:179], v[148:151], v[94:97]
	global_load_lds_dwordx4 v[198:199], off
	v_mfma_f32_16x16x32_bf16 v[78:81], v[176:179], v[152:155], v[78:81]
	v_lshl_add_u64 v[198:199], v[198:199], 0, s[98:99]
	s_add_i32 m0, s13, 0x800
	s_waitcnt lgkmcnt(6)
	v_mfma_f32_16x16x32_bf16 v[122:125], v[180:183], v[140:143], v[122:125]
	global_load_lds_dwordx4 v[200:201], off
	v_mfma_f32_16x16x32_bf16 v[106:109], v[180:183], v[144:147], v[106:109]
	v_lshl_add_u64 v[200:201], v[200:201], 0, s[98:99]
	s_add_i32 m0, s13, 0xc00
	v_mfma_f32_16x16x32_bf16 v[90:93], v[180:183], v[148:151], v[90:93]
	global_load_lds_dwordx4 v[202:203], off
	v_mfma_f32_16x16x32_bf16 v[74:77], v[180:183], v[152:155], v[74:77]
	v_lshl_add_u64 v[202:203], v[202:203], 0, s[98:99]
	s_mov_b32 m0, s12
	s_waitcnt lgkmcnt(5)
	v_mfma_f32_16x16x32_bf16 v[118:121], v[184:187], v[140:143], v[118:121]
	global_load_lds_dwordx4 v[204:205], off
	v_mfma_f32_16x16x32_bf16 v[102:105], v[184:187], v[144:147], v[102:105]
	v_lshl_add_u64 v[204:205], v[204:205], 0, s[98:99]
	s_add_i32 m0, s12, 0x400
	v_mfma_f32_16x16x32_bf16 v[86:89], v[184:187], v[148:151], v[86:89]
	global_load_lds_dwordx4 v[206:207], off
	v_mfma_f32_16x16x32_bf16 v[70:73], v[184:187], v[152:155], v[70:73]
	v_lshl_add_u64 v[206:207], v[206:207], 0, s[98:99]
	s_waitcnt lgkmcnt(4)
	v_mfma_f32_16x16x32_bf16 v[114:117], v[188:191], v[140:143], v[114:117]
	s_add_i32 s13, s11, 0x6000
	v_mfma_f32_16x16x32_bf16 v[98:101], v[188:191], v[144:147], v[98:101]
	s_cmp_eq_u32 s11, 0xc000
	s_cselect_b32 s11, 0, s13
	v_mfma_f32_16x16x32_bf16 v[82:85], v[188:191], v[148:151], v[82:85]
	v_add_u32_e32 v192, s11, v160
	v_mfma_f32_16x16x32_bf16 v[66:69], v[188:191], v[152:155], v[66:69]
	v_add_u32_e32 v193, s11, v0
	s_waitcnt vmcnt(6) lgkmcnt(0)
	s_barrier
	v_mfma_f32_16x16x32_bf16 v[62:65], v[176:179], v[156:159], v[62:65]
	ds_read_b128 v[140:143], v192
	v_mfma_f32_16x16x32_bf16 v[46:49], v[176:179], v[164:167], v[46:49]
	ds_read_b128 v[144:147], v192 offset:1024
	v_mfma_f32_16x16x32_bf16 v[30:33], v[176:179], v[168:171], v[30:33]
	ds_read_b128 v[148:151], v192 offset:2048
	v_mfma_f32_16x16x32_bf16 v[14:17], v[176:179], v[172:175], v[14:17]
	ds_read_b128 v[152:155], v192 offset:3072
	ds_read_b128 v[176:179], v193 offset:16384
	v_mfma_f32_16x16x32_bf16 v[58:61], v[180:183], v[156:159], v[58:61]
	v_mfma_f32_16x16x32_bf16 v[42:45], v[180:183], v[164:167], v[42:45]
	v_mfma_f32_16x16x32_bf16 v[26:29], v[180:183], v[168:171], v[26:29]
	v_mfma_f32_16x16x32_bf16 v[10:13], v[180:183], v[172:175], v[10:13]
	ds_read_b128 v[180:183], v193 offset:17408
	v_mfma_f32_16x16x32_bf16 v[54:57], v[184:187], v[156:159], v[54:57]
	v_mfma_f32_16x16x32_bf16 v[38:41], v[184:187], v[164:167], v[38:41]
	v_mfma_f32_16x16x32_bf16 v[22:25], v[184:187], v[168:171], v[22:25]
	v_mfma_f32_16x16x32_bf16 v[6:9], v[184:187], v[172:175], v[6:9]
	ds_read_b128 v[184:187], v193 offset:18432
	v_mfma_f32_16x16x32_bf16 v[50:53], v[188:191], v[156:159], v[50:53]
	v_mfma_f32_16x16x32_bf16 v[34:37], v[188:191], v[164:167], v[34:37]
	v_mfma_f32_16x16x32_bf16 v[18:21], v[188:191], v[168:171], v[18:21]
	v_mfma_f32_16x16x32_bf16 v[2:5], v[188:191], v[172:175], v[2:5]
	ds_read_b128 v[188:191], v193 offset:19456
	s_sub_i32 s100, s100, 1
	s_cmp_lg_u32 s100, 0
	s_cbranch_scc1 .Lpipe_mlp2
	v_add_u32_e32 v161, s11, v160
	ds_read_b128 v[156:159], v161 offset:4096
	ds_read_b128 v[164:167], v161 offset:5120
	ds_read_b128 v[168:171], v161 offset:6144
	ds_read_b128 v[172:175], v161 offset:7168
	s_add_i32 s12, s11, 0xffffa000
	s_cmp_eq_u32 s11, 0
	s_cselect_b32 s12, 0xc000, s12
	s_add_i32 s13, s12, s0
	s_add_i32 s12, s12, s1
	s_mov_b32 m0, s13
	s_waitcnt lgkmcnt(7)
	v_mfma_f32_16x16x32_bf16 v[126:129], v[176:179], v[140:143], v[126:129]
	global_load_lds_dwordx4 v[196:197], off
	v_mfma_f32_16x16x32_bf16 v[110:113], v[176:179], v[144:147], v[110:113]
	v_lshl_add_u64 v[196:197], v[196:197], 0, s[98:99]
	s_add_i32 m0, s13, 0x400
	v_mfma_f32_16x16x32_bf16 v[94:97], v[176:179], v[148:151], v[94:97]
	global_load_lds_dwordx4 v[198:199], off
	v_mfma_f32_16x16x32_bf16 v[78:81], v[176:179], v[152:155], v[78:81]
	v_lshl_add_u64 v[198:199], v[198:199], 0, s[98:99]
	s_add_i32 m0, s13, 0x800
	s_waitcnt lgkmcnt(6)
	v_mfma_f32_16x16x32_bf16 v[122:125], v[180:183], v[140:143], v[122:125]
	global_load_lds_dwordx4 v[200:201], off
	v_mfma_f32_16x16x32_bf16 v[106:109], v[180:183], v[144:147], v[106:109]
	v_lshl_add_u64 v[200:201], v[200:201], 0, s[98:99]
	s_add_i32 m0, s13, 0xc00
	v_mfma_f32_16x16x32_bf16 v[90:93], v[180:183], v[148:151], v[90:93]
	global_load_lds_dwordx4 v[202:203], off
	v_mfma_f32_16x16x32_bf16 v[74:77], v[180:183], v[152:155], v[74:77]
	v_lshl_add_u64 v[202:203], v[202:203], 0, s[98:99]
	s_mov_b32 m0, s12
	s_waitcnt lgkmcnt(5)
; template <int MI, int NI>
; DI void gemm256(f32x4 (&acc)[MI][NI], const u16* __restrict__ A, int lda, const u16* __restrict__ Bt, int ldb, int K, int m0, int n0, char* smem) {
;     ...
;   for (int kt = 0; kt < nk; ++kt) {
;     if (kt + 1 < nk) asm volatile("s_waitcnt vmcnt(%0) lgkmcnt(0)" :: "n"(LPS) : "memory");
;     else asm volatile("s_waitcnt vmcnt(0) lgkmcnt(0)" ::: "memory");
;     __builtin_amdgcn_s_barrier();
;     __builtin_amdgcn_s_setprio(1);
;     const char* sb = smem + st * STAGE + foff;
;     bf16x8 af[MI], bfr[NI];
; #pragma unroll
;     for (int mi = 0; mi < MI; ++mi) af[mi] = *(const bf16x8*)(sb + (wr * MI + mi) * 1024);
; #pragma unroll
;     for (int ni = 0; ni < NI; ++ni) bfr[ni] = *(const bf16x8*)(sb + ABYTES + (wc * NI + ni) * 1024);
;     __builtin_amdgcn_sched_barrier(0x0);
;     if (kt + 2 < nk) { const int s2 = st >= 1 ? st - 1 : 2; G256_ISSUE(s2, (kt + 2) * 32); }
;     __builtin_amdgcn_s_setprio(0);
; #pragma unroll
;     for (int mi = 0; mi < MI; ++mi)
; #pragma unroll
;       for (int ni = 0; ni < NI; ++ni)
;         acc[mi][ni] = __builtin_amdgcn_mfma_f32_16x16x32_bf16(bfr[ni], af[mi], acc[mi][ni], 0, 0, 0);
;     st = st == 2 ? 0 : st + 1;
;   }
;   asm volatile("s_waitcnt lgkmcnt(0)" ::: "memory");
;   __builtin_amdgcn_s_barrier();
	v_mfma_f32_16x16x32_bf16 v[118:121], v[184:187], v[140:143], v[118:121]
	global_load_lds_dwordx4 v[204:205], off
	v_mfma_f32_16x16x32_bf16 v[102:105], v[184:187], v[144:147], v[102:105]
	v_lshl_add_u64 v[204:205], v[204:205], 0, s[98:99]
	s_add_i32 m0, s12, 0x400
	v_mfma_f32_16x16x32_bf16 v[86:89], v[184:187], v[148:151], v[86:89]
	global_load_lds_dwordx4 v[206:207], off
	v_mfma_f32_16x16x32_bf16 v[70:73], v[184:187], v[152:155], v[70:73]
	v_lshl_add_u64 v[206:207], v[206:207], 0, s[98:99]
	s_waitcnt lgkmcnt(4)
	v_mfma_f32_16x16x32_bf16 v[114:117], v[188:191], v[140:143], v[114:117]
	v_mfma_f32_16x16x32_bf16 v[98:101], v[188:191], v[144:147], v[98:101]
	v_mfma_f32_16x16x32_bf16 v[82:85], v[188:191], v[148:151], v[82:85]
	v_mfma_f32_16x16x32_bf16 v[66:69], v[188:191], v[152:155], v[66:69]
	s_waitcnt lgkmcnt(0)
	v_mfma_f32_16x16x32_bf16 v[62:65], v[176:179], v[156:159], v[62:65]
	v_mfma_f32_16x16x32_bf16 v[46:49], v[176:179], v[164:167], v[46:49]
	v_mfma_f32_16x16x32_bf16 v[30:33], v[176:179], v[168:171], v[30:33]
	v_mfma_f32_16x16x32_bf16 v[14:17], v[176:179], v[172:175], v[14:17]
	v_mfma_f32_16x16x32_bf16 v[58:61], v[180:183], v[156:159], v[58:61]
	v_mfma_f32_16x16x32_bf16 v[42:45], v[180:183], v[164:167], v[42:45]
	v_mfma_f32_16x16x32_bf16 v[26:29], v[180:183], v[168:171], v[26:29]
	v_mfma_f32_16x16x32_bf16 v[10:13], v[180:183], v[172:175], v[10:13]
	v_mfma_f32_16x16x32_bf16 v[54:57], v[184:187], v[156:159], v[54:57]
	v_mfma_f32_16x16x32_bf16 v[38:41], v[184:187], v[164:167], v[38:41]
	v_mfma_f32_16x16x32_bf16 v[22:25], v[184:187], v[168:171], v[22:25]
	v_mfma_f32_16x16x32_bf16 v[6:9], v[184:187], v[172:175], v[6:9]
	v_mfma_f32_16x16x32_bf16 v[50:53], v[188:191], v[156:159], v[50:53]
	v_mfma_f32_16x16x32_bf16 v[34:37], v[188:191], v[164:167], v[34:37]
	v_mfma_f32_16x16x32_bf16 v[18:21], v[188:191], v[168:171], v[18:21]
	v_mfma_f32_16x16x32_bf16 v[2:5], v[188:191], v[172:175], v[2:5]
	s_mov_b32 s10, 0
	s_waitcnt vmcnt(6) lgkmcnt(0)
	s_barrier
	s_setprio 1
	s_mul_i32 s0, s10, 0x6000
	v_or_b32_e32 v0, s0, v138
	v_add_u32_e32 v136, v0, v139
	ds_read_b128 v[130:133], v136
	ds_read_b128 v[140:143], v136 offset:1024
	ds_read_b128 v[144:147], v136 offset:2048
	ds_read_b128 v[148:151], v136 offset:3072
	ds_read_b128 v[152:155], v136 offset:4096
	ds_read_b128 v[156:159], v136 offset:5120
	ds_read_b128 v[164:167], v136 offset:6144
	ds_read_b128 v[168:171], v136 offset:7168
	v_add_u32_e32 v0, v0, v135
	ds_read_b128 v[172:175], v0 offset:16384
	ds_read_b128 v[176:179], v0 offset:17408
	ds_read_b128 v[180:183], v0 offset:18432
	ds_read_b128 v[184:187], v0 offset:19456
	v_bfe_u32 v0, v134, 6, 1
	s_setprio 0
	s_waitcnt vmcnt(0) lgkmcnt(0)
	s_waitcnt lgkmcnt(3)
	v_mfma_f32_16x16x32_bf16 v[126:129], v[172:175], v[130:133], v[126:129]
	v_ashrrev_i32_e32 v160, 7, v134
	v_and_b32_e32 v161, 15, v134
	v_bfe_u32 v134, v134, 4, 2
	s_waitcnt lgkmcnt(2)
	v_mfma_f32_16x16x32_bf16 v[122:125], v[176:179], v[130:133], v[122:125]
	s_barrier
	s_waitcnt lgkmcnt(1)
	v_mfma_f32_16x16x32_bf16 v[118:121], v[180:183], v[130:133], v[118:121]
	s_waitcnt lgkmcnt(0)
	v_mfma_f32_16x16x32_bf16 v[114:117], v[184:187], v[130:133], v[114:117]
	v_mfma_f32_16x16x32_bf16 v[110:113], v[172:175], v[140:143], v[110:113]
	v_mfma_f32_16x16x32_bf16 v[106:109], v[176:179], v[140:143], v[106:109]
	v_mfma_f32_16x16x32_bf16 v[102:105], v[180:183], v[140:143], v[102:105]
	v_mfma_f32_16x16x32_bf16 v[98:101], v[184:187], v[140:143], v[98:101]
	v_mfma_f32_16x16x32_bf16 v[94:97], v[172:175], v[144:147], v[94:97]
	v_mfma_f32_16x16x32_bf16 v[90:93], v[176:179], v[144:147], v[90:93]
	v_mfma_f32_16x16x32_bf16 v[86:89], v[180:183], v[144:147], v[86:89]
	v_mfma_f32_16x16x32_bf16 v[82:85], v[184:187], v[144:147], v[82:85]
	v_mfma_f32_16x16x32_bf16 v[78:81], v[172:175], v[148:151], v[78:81]
	v_mfma_f32_16x16x32_bf16 v[130:133], v[176:179], v[148:151], v[74:77]
	v_mfma_f32_16x16x32_bf16 v[70:73], v[180:183], v[148:151], v[70:73]
	v_mfma_f32_16x16x32_bf16 v[66:69], v[184:187], v[148:151], v[66:69]
	v_mfma_f32_16x16x32_bf16 v[62:65], v[172:175], v[152:155], v[62:65]
	v_mfma_f32_16x16x32_bf16 v[58:61], v[176:179], v[152:155], v[58:61]
	v_mfma_f32_16x16x32_bf16 v[54:57], v[180:183], v[152:155], v[54:57]
	v_mfma_f32_16x16x32_bf16 v[50:53], v[184:187], v[152:155], v[50:53]
	v_mfma_f32_16x16x32_bf16 v[46:49], v[172:175], v[156:159], v[46:49]
	v_mfma_f32_16x16x32_bf16 v[42:45], v[176:179], v[156:159], v[42:45]
	v_mfma_f32_16x16x32_bf16 v[38:41], v[180:183], v[156:159], v[38:41]
	v_mfma_f32_16x16x32_bf16 v[34:37], v[184:187], v[156:159], v[34:37]
	v_mfma_f32_16x16x32_bf16 v[30:33], v[172:175], v[164:167], v[30:33]
	v_mfma_f32_16x16x32_bf16 v[26:29], v[176:179], v[164:167], v[26:29]
	v_mfma_f32_16x16x32_bf16 v[22:25], v[180:183], v[164:167], v[22:25]
	v_mfma_f32_16x16x32_bf16 v[18:21], v[184:187], v[164:167], v[18:21]
	v_mfma_f32_16x16x32_bf16 v[14:17], v[172:175], v[168:171], v[14:17]
	v_mfma_f32_16x16x32_bf16 v[10:13], v[176:179], v[168:171], v[10:13]
	v_mfma_f32_16x16x32_bf16 v[6:9], v[180:183], v[168:171], v[6:9]
	v_mfma_f32_16x16x32_bf16 v[140:143], v[184:187], v[168:171], v[2:5]
	s_setprio 1
	s_addk_i32 s0, 0x6000
	s_cmp_lg_u32 s10, 2
	s_cselect_b32 s0, s0, 0
	v_or_b32_e32 v168, s0, v138
	v_add_u32_e32 v164, v168, v139
	ds_read_b128 v[2:5], v164
	ds_read_b128 v[74:77], v164 offset:1024
	ds_read_b128 v[136:139], v164 offset:2048
	ds_read_b128 v[144:147], v164 offset:3072
	ds_read_b128 v[148:151], v164 offset:4096
	ds_read_b128 v[152:155], v164 offset:5120
	ds_read_b128 v[156:159], v164 offset:6144
	ds_read_b128 v[164:167], v164 offset:7168
	v_add_u32_e32 v135, v168, v135
	ds_read_b128 v[168:171], v135 offset:16384
	ds_read_b128 v[172:175], v135 offset:17408
	ds_read_b128 v[176:179], v135 offset:18432
	ds_read_b128 v[180:183], v135 offset:19456
	s_setprio 0
	s_waitcnt lgkmcnt(3)
	v_mfma_f32_16x16x32_bf16 v[126:129], v[168:171], v[2:5], v[126:129]
	s_waitcnt lgkmcnt(0)
	s_barrier
; #define EPI_BEGIN const int lr1_ = launder_v(lr), lq1_ = launder_v(lq), wr1_ = launder_v(wr), wc1_ = launder_v(wc); { const int lr = lr1_, lq = lq1_, wr = wr1_, wc = wc1_; (void)lr; (void)lq; (void)wr; (void)wc;
; template <int MI, int NI>
; DI void resid_tile(const u16* A, int K, const u16* Bt, const float* gate, const float* xl_in, const float* xc_in, float* xl_out, float* xc_out,
;                    int m0, int n0, char* smem) {
;     ...
;   EPI_BEGIN
; #pragma unroll
;   for (int mi = 0; mi < MI; ++mi) {
;     const int m = m0 + wr * 16 * MI + mi * 16 + lr;
;     const int b9 = m < NTL ? m >> 12 : 8;
;     const float* xi = xrow(xl_in, xc_in, m);
;     float* xo = m < NTL ? xl_out + (size_t)m * D : xc_out + (size_t)(m - NTL) * D;
; #pragma unroll
;     for (int ni = 0; ni < NI; ++ni) {
;       const int n = n0 + wc * 16 * NI + ni * 16 + lq * 4;
;       const float4 g = *(const float4*)(gate + (size_t)b9 * 6144 + n);
;       const float4 xv = *(const float4*)(xi + n);
;       float4 ov;
;       ov.x = xv.x + g.x * acc[mi][ni][0]; ov.y = xv.y + g.y * acc[mi][ni][1]; ov.z = xv.z + g.z * acc[mi][ni][2]; ov.w = xv.w + g.w * acc[mi][ni][3];
;       *(float4*)(xo + n) = ov;
;     }
	s_waitcnt lgkmcnt(2)
	v_mfma_f32_16x16x32_bf16 v[122:125], v[172:175], v[2:5], v[122:125]
	s_waitcnt lgkmcnt(1)
	v_mfma_f32_16x16x32_bf16 v[184:187], v[176:179], v[2:5], v[118:121]
	v_lshlrev_b32_e32 v0, 6, v0
	s_waitcnt lgkmcnt(0)
	v_mfma_f32_16x16x32_bf16 v[188:191], v[180:183], v[2:5], v[114:117]
	v_lshlrev_b32_e32 v2, 7, v160
	v_mov_b32_e32 v118, s95
	v_mov_b32_e32 v119, s49
	v_add3_u32 v116, v161, s8, v2
	v_lshlrev_b32_e32 v2, 2, v134
	v_add3_u32 v2, v2, s9, v0
	v_min_i32_e32 v0, 0x8000, v116
	v_mfma_f32_16x16x32_bf16 v[110:113], v[168:171], v[74:77], v[110:113]
	v_ashrrev_i32_e32 v117, 31, v116
	v_cmp_gt_i32_e32 vcc, s58, v116
	v_mov_b32_e32 v120, s94
	v_mfma_f32_16x16x32_bf16 v[106:109], v[172:175], v[74:77], v[106:109]
	v_cndmask_b32_e32 v5, 0, v117, vcc
	v_mov_b32_e32 v121, s48
	v_cndmask_b32_e32 v115, v118, v119, vcc
	v_mfma_f32_16x16x32_bf16 v[102:105], v[176:179], v[74:77], v[102:105]
	v_cndmask_b32_e32 v114, v120, v121, vcc
	v_ashrrev_i32_e32 v3, 31, v2
	v_mfma_f32_16x16x32_bf16 v[98:101], v[180:183], v[74:77], v[98:101]
	v_mfma_f32_16x16x32_bf16 v[74:77], v[168:171], v[144:147], v[78:81]
	v_mfma_f32_16x16x32_bf16 v[78:81], v[172:175], v[144:147], v[130:133]
	s_nop 2
	v_ashrrev_i32_e32 v130, 12, v0
	v_add_u32_e32 v0, 0xffff8000, v116
	v_cndmask_b32_e32 v4, v0, v116, vcc
	v_lshlrev_b64 v[4:5], 12, v[4:5]
	v_lshl_add_u64 v[4:5], v[114:115], 0, v[4:5]
	v_mul_hi_i32_i24_e32 v115, 0x6000, v130
	v_mul_i32_i24_e32 v114, 0x6000, v130
	v_lshl_add_u64 v[130:131], s[82:83], 0, v[114:115]
	v_lshlrev_b64 v[114:115], 2, v[2:3]
	v_mfma_f32_16x16x32_bf16 v[94:97], v[168:171], v[136:139], v[94:97]
	v_lshl_add_u64 v[134:135], v[130:131], 0, v[114:115]
	v_mfma_f32_16x16x32_bf16 v[90:93], v[172:175], v[136:139], v[90:93]
	v_mfma_f32_16x16x32_bf16 v[86:89], v[176:179], v[136:139], v[86:89]
	v_mfma_f32_16x16x32_bf16 v[82:85], v[180:183], v[136:139], v[82:85]
	v_lshl_add_u64 v[136:137], v[4:5], 0, v[114:115]
	flat_load_dwordx4 v[2:5], v[134:135]
	flat_load_dwordx4 v[130:133], v[136:137]
	v_mfma_f32_16x16x32_bf16 v[70:73], v[176:179], v[144:147], v[70:73]
	v_lshlrev_b64 v[138:139], 12, v[116:117]
	v_lshl_add_u64 v[138:139], s[48:49], 0, v[138:139]
	s_waitcnt vmcnt(0) lgkmcnt(0)
	v_pk_fma_f32 v[2:3], v[126:127], v[2:3], v[130:131]
	v_mfma_f32_16x16x32_bf16 v[66:69], v[180:183], v[144:147], v[66:69]
	v_lshlrev_b64 v[144:145], 12, v[0:1]
	v_lshl_add_u64 v[144:145], s[94:95], 0, v[144:145]
	v_cndmask_b32_e32 v139, v145, v139, vcc
	v_cndmask_b32_e32 v138, v144, v138, vcc
	v_lshl_add_u64 v[138:139], v[138:139], 0, v[114:115]
	v_pk_fma_f32 v[4:5], v[128:129], v[4:5], v[132:133]
	flat_store_dwordx4 v[138:139], v[2:5]
	flat_load_dwordx4 v[126:129], v[134:135] offset:64
	flat_load_dwordx4 v[130:133], v[136:137] offset:64
	v_mfma_f32_16x16x32_bf16 v[2:5], v[172:175], v[164:167], v[10:13]
	v_mfma_f32_16x16x32_bf16 v[62:65], v[168:171], v[148:151], v[62:65]
	s_waitcnt vmcnt(0) lgkmcnt(0)
	s_nop 0
	v_pk_fma_f32 v[10:11], v[122:123], v[126:127], v[130:131]
	v_pk_fma_f32 v[12:13], v[124:125], v[128:129], v[132:133]
	flat_store_dwordx4 v[138:139], v[10:13] offset:64
	flat_load_dwordx4 v[10:13], v[134:135] offset:128
	s_nop 0
	flat_load_dwordx4 v[122:125], v[136:137] offset:128
	v_mfma_f32_16x16x32_bf16 v[58:61], v[172:175], v[148:151], v[58:61]
	s_waitcnt vmcnt(0) lgkmcnt(0)
	v_pk_fma_f32 v[10:11], v[184:185], v[10:11], v[122:123]
	v_pk_fma_f32 v[12:13], v[186:187], v[12:13], v[124:125]
	flat_store_dwordx4 v[138:139], v[10:13] offset:128
	flat_load_dwordx4 v[122:125], v[134:135] offset:192
	flat_load_dwordx4 v[126:129], v[136:137] offset:192
	v_mfma_f32_16x16x32_bf16 v[54:57], v[176:179], v[148:151], v[54:57]
	s_waitcnt vmcnt(0) lgkmcnt(0)
	v_pk_fma_f32 v[122:123], v[188:189], v[122:123], v[126:127]
	v_pk_fma_f32 v[124:125], v[190:191], v[124:125], v[128:129]
	v_mfma_f32_16x16x32_bf16 v[50:53], v[180:183], v[148:151], v[50:53]
	flat_store_dwordx4 v[138:139], v[122:125] offset:192
	v_mfma_f32_16x16x32_bf16 v[46:49], v[168:171], v[152:155], v[46:49]
	v_mfma_f32_16x16x32_bf16 v[42:45], v[172:175], v[152:155], v[42:45]
	v_mfma_f32_16x16x32_bf16 v[38:41], v[176:179], v[152:155], v[38:41]
	v_mfma_f32_16x16x32_bf16 v[34:37], v[180:183], v[152:155], v[34:37]
	v_mfma_f32_16x16x32_bf16 v[30:33], v[168:171], v[156:159], v[30:33]
	v_mfma_f32_16x16x32_bf16 v[26:29], v[172:175], v[156:159], v[26:29]
	v_mfma_f32_16x16x32_bf16 v[22:25], v[176:179], v[156:159], v[22:25]
	v_mfma_f32_16x16x32_bf16 v[18:21], v[180:183], v[156:159], v[18:21]
	v_mfma_f32_16x16x32_bf16 v[14:17], v[168:171], v[164:167], v[14:17]
	v_mfma_f32_16x16x32_bf16 v[6:9], v[176:179], v[164:167], v[6:9]
	v_mfma_f32_16x16x32_bf16 v[10:13], v[180:183], v[164:167], v[140:143]
	v_add_u32_e32 v122, 16, v116
	v_min_i32_e32 v0, 0x8000, v122
	v_cmp_gt_i32_e32 vcc, s58, v122
	v_ashrrev_i32_e32 v117, 12, v0
	v_add_u32_e32 v0, 0xffff8010, v116
	v_ashrrev_i32_e32 v123, 31, v122
	v_cndmask_b32_e32 v125, 0, v123, vcc
	v_cndmask_b32_e32 v124, v0, v122, vcc
	v_cndmask_b32_e32 v127, v118, v119, vcc
	v_cndmask_b32_e32 v126, v120, v121, vcc
	v_lshlrev_b64 v[124:125], 12, v[124:125]
	v_lshl_add_u64 v[124:125], v[126:127], 0, v[124:125]
	v_lshlrev_b64 v[122:123], 12, v[122:123]
	v_lshlrev_b64 v[126:127], 12, v[0:1]
	v_lshl_add_u64 v[122:123], s[48:49], 0, v[122:123]
	v_lshl_add_u64 v[126:127], s[94:95], 0, v[126:127]
	v_cndmask_b32_e32 v123, v127, v123, vcc
	v_cndmask_b32_e32 v122, v126, v122, vcc
	v_mul_hi_i32_i24_e32 v127, 0x6000, v117
	v_mul_i32_i24_e32 v126, 0x6000, v117
	v_lshl_add_u64 v[126:127], s[82:83], 0, v[126:127]
	v_lshl_add_u64 v[130:131], v[126:127], 0, v[114:115]
	v_lshl_add_u64 v[132:133], v[124:125], 0, v[114:115]
	v_lshl_add_u64 v[134:135], v[122:123], 0, v[114:115]
	global_load_dwordx4 v[156:159], v[130:131], off
	global_load_dwordx4 v[164:167], v[130:131], off offset:64
	global_load_dwordx4 v[168:171], v[130:131], off offset:128
	global_load_dwordx4 v[172:175], v[130:131], off offset:192
	global_load_dwordx4 v[140:143], v[132:133], off
	global_load_dwordx4 v[144:147], v[132:133], off offset:64
	global_load_dwordx4 v[148:151], v[132:133], off offset:128
	global_load_dwordx4 v[152:155], v[132:133], off offset:192
	v_mov_b32_e32 v216, 0x10000
	v_mov_b32_e32 v217, 0
	v_lshl_add_u64 v[212:213], v[132:133], 0, v[216:217]
	v_lshl_add_u64 v[214:215], v[134:135], 0, v[216:217]
	global_load_dwordx4 v[176:179], v[212:213], off
	global_load_dwordx4 v[180:183], v[212:213], off offset:64
	global_load_dwordx4 v[184:187], v[212:213], off offset:128
	global_load_dwordx4 v[188:191], v[212:213], off offset:192
	v_lshl_add_u64 v[212:213], v[212:213], 0, v[216:217]
	s_waitcnt vmcnt(4)
; #define LAUNDER_IDS const int tid__ = launder_v((int)threadIdx.x); const int blk__ = launder_s((int)blockIdx.x); (void)tid__; (void)blk__;
; template <int MI, int NI>
; DI void resid_tile(const u16* A, int K, const u16* Bt, const float* gate, const float* xl_in, const float* xc_in, float* xl_out, float* xc_out,
;                    int m0, int n0, char* smem) {
;     ...
; #pragma unroll
;   for (int mi = 0; mi < MI; ++mi) {
;     const int m = m0 + wr * 16 * MI + mi * 16 + lr;
;     const int b9 = m < NTL ? m >> 12 : 8;
;     const float* xi = xrow(xl_in, xc_in, m);
;     float* xo = m < NTL ? xl_out + (size_t)m * D : xc_out + (size_t)(m - NTL) * D;
; #pragma unroll
;     for (int ni = 0; ni < NI; ++ni) {
;       const int n = n0 + wc * 16 * NI + ni * 16 + lq * 4;
;       const float4 g = *(const float4*)(gate + (size_t)b9 * 6144 + n);
;       const float4 xv = *(const float4*)(xi + n);
;       float4 ov;
;       ov.x = xv.x + g.x * acc[mi][ni][0]; ov.y = xv.y + g.y * acc[mi][ni][1]; ov.z = xv.z + g.z * acc[mi][ni][2]; ov.w = xv.w + g.w * acc[mi][ni][3];
;       *(float4*)(xo + n) = ov;
;     }
;     __builtin_amdgcn_sched_barrier(0);
;   }
;   EPI_END
; }
; DI void phase_resid(const Params& p, const u16* A, int K, const u16* Bt, const float* gate  ,
;                     const float* xl_in, const float* xc_in, float* xl_out, float* xc_out, int Mout, char* smem) {
;   LAUNDER_IDS
;   for (int it = 0;; ++it) {
;     int tm, tn;
;     if (!tile_map(it, NTL / 256, 8, blk__, gridDim.x, tm, tn)) break;
;     resid_tile<8, 4>(A, K, Bt, gate, xl_in, xc_in, xl_out, xc_out, tm * 256, tn * 128, smem);
;   }
	v_pk_fma_f32 v[110:111], v[110:111], v[156:157], v[140:141]
	v_pk_fma_f32 v[112:113], v[112:113], v[158:159], v[142:143]
	v_pk_fma_f32 v[106:107], v[106:107], v[164:165], v[144:145]
	v_pk_fma_f32 v[108:109], v[108:109], v[166:167], v[146:147]
	v_pk_fma_f32 v[102:103], v[102:103], v[168:169], v[148:149]
	v_pk_fma_f32 v[104:105], v[104:105], v[170:171], v[150:151]
	v_pk_fma_f32 v[98:99], v[98:99], v[172:173], v[152:153]
	v_pk_fma_f32 v[100:101], v[100:101], v[174:175], v[154:155]
	global_store_dwordx4 v[134:135], v[110:113], off
	global_store_dwordx4 v[134:135], v[106:109], off offset:64
	global_store_dwordx4 v[134:135], v[102:105], off offset:128
	global_store_dwordx4 v[134:135], v[98:101], off offset:192
	global_load_dwordx4 v[140:143], v[212:213], off
	global_load_dwordx4 v[144:147], v[212:213], off offset:64
	global_load_dwordx4 v[148:151], v[212:213], off offset:128
	global_load_dwordx4 v[152:155], v[212:213], off offset:192
	v_lshl_add_u64 v[212:213], v[212:213], 0, v[216:217]
	s_waitcnt vmcnt(8)
	v_pk_fma_f32 v[94:95], v[94:95], v[156:157], v[176:177]
	v_pk_fma_f32 v[96:97], v[96:97], v[158:159], v[178:179]
	v_pk_fma_f32 v[90:91], v[90:91], v[164:165], v[180:181]
	v_pk_fma_f32 v[92:93], v[92:93], v[166:167], v[182:183]
	v_pk_fma_f32 v[86:87], v[86:87], v[168:169], v[184:185]
	v_pk_fma_f32 v[88:89], v[88:89], v[170:171], v[186:187]
	v_pk_fma_f32 v[82:83], v[82:83], v[172:173], v[188:189]
	v_pk_fma_f32 v[84:85], v[84:85], v[174:175], v[190:191]
	global_store_dwordx4 v[214:215], v[94:97], off
	global_store_dwordx4 v[214:215], v[90:93], off offset:64
	global_store_dwordx4 v[214:215], v[86:89], off offset:128
	global_store_dwordx4 v[214:215], v[82:85], off offset:192
	v_lshl_add_u64 v[214:215], v[214:215], 0, v[216:217]
	global_load_dwordx4 v[176:179], v[212:213], off
	global_load_dwordx4 v[180:183], v[212:213], off offset:64
	global_load_dwordx4 v[184:187], v[212:213], off offset:128
	global_load_dwordx4 v[188:191], v[212:213], off offset:192
	v_lshl_add_u64 v[212:213], v[212:213], 0, v[216:217]
	s_waitcnt vmcnt(8)
	v_pk_fma_f32 v[74:75], v[74:75], v[156:157], v[140:141]
	v_pk_fma_f32 v[76:77], v[76:77], v[158:159], v[142:143]
	v_pk_fma_f32 v[78:79], v[78:79], v[164:165], v[144:145]
	v_pk_fma_f32 v[80:81], v[80:81], v[166:167], v[146:147]
	v_pk_fma_f32 v[70:71], v[70:71], v[168:169], v[148:149]
	v_pk_fma_f32 v[72:73], v[72:73], v[170:171], v[150:151]
	v_pk_fma_f32 v[66:67], v[66:67], v[172:173], v[152:153]
	v_pk_fma_f32 v[68:69], v[68:69], v[174:175], v[154:155]
	global_store_dwordx4 v[214:215], v[74:77], off
	global_store_dwordx4 v[214:215], v[78:81], off offset:64
	global_store_dwordx4 v[214:215], v[70:73], off offset:128
	global_store_dwordx4 v[214:215], v[66:69], off offset:192
	v_lshl_add_u64 v[214:215], v[214:215], 0, v[216:217]
	global_load_dwordx4 v[140:143], v[212:213], off
	global_load_dwordx4 v[144:147], v[212:213], off offset:64
	global_load_dwordx4 v[148:151], v[212:213], off offset:128
	global_load_dwordx4 v[152:155], v[212:213], off offset:192
	v_lshl_add_u64 v[212:213], v[212:213], 0, v[216:217]
	s_waitcnt vmcnt(8)
	v_pk_fma_f32 v[62:63], v[62:63], v[156:157], v[176:177]
	v_pk_fma_f32 v[64:65], v[64:65], v[158:159], v[178:179]
	v_pk_fma_f32 v[58:59], v[58:59], v[164:165], v[180:181]
	v_pk_fma_f32 v[60:61], v[60:61], v[166:167], v[182:183]
	v_pk_fma_f32 v[54:55], v[54:55], v[168:169], v[184:185]
	v_pk_fma_f32 v[56:57], v[56:57], v[170:171], v[186:187]
	v_pk_fma_f32 v[50:51], v[50:51], v[172:173], v[188:189]
	v_pk_fma_f32 v[52:53], v[52:53], v[174:175], v[190:191]
	global_store_dwordx4 v[214:215], v[62:65], off
	global_store_dwordx4 v[214:215], v[58:61], off offset:64
	global_store_dwordx4 v[214:215], v[54:57], off offset:128
	global_store_dwordx4 v[214:215], v[50:53], off offset:192
	v_lshl_add_u64 v[214:215], v[214:215], 0, v[216:217]
	global_load_dwordx4 v[176:179], v[212:213], off
	global_load_dwordx4 v[180:183], v[212:213], off offset:64
	global_load_dwordx4 v[184:187], v[212:213], off offset:128
	global_load_dwordx4 v[188:191], v[212:213], off offset:192
	v_lshl_add_u64 v[212:213], v[212:213], 0, v[216:217]
	s_waitcnt vmcnt(8)
	v_pk_fma_f32 v[46:47], v[46:47], v[156:157], v[140:141]
	v_pk_fma_f32 v[48:49], v[48:49], v[158:159], v[142:143]
	v_pk_fma_f32 v[42:43], v[42:43], v[164:165], v[144:145]
	v_pk_fma_f32 v[44:45], v[44:45], v[166:167], v[146:147]
	v_pk_fma_f32 v[38:39], v[38:39], v[168:169], v[148:149]
	v_pk_fma_f32 v[40:41], v[40:41], v[170:171], v[150:151]
	v_pk_fma_f32 v[34:35], v[34:35], v[172:173], v[152:153]
	v_pk_fma_f32 v[36:37], v[36:37], v[174:175], v[154:155]
	global_store_dwordx4 v[214:215], v[46:49], off
	global_store_dwordx4 v[214:215], v[42:45], off offset:64
	global_store_dwordx4 v[214:215], v[38:41], off offset:128
	global_store_dwordx4 v[214:215], v[34:37], off offset:192
	v_lshl_add_u64 v[214:215], v[214:215], 0, v[216:217]
	global_load_dwordx4 v[140:143], v[212:213], off
	global_load_dwordx4 v[144:147], v[212:213], off offset:64
	global_load_dwordx4 v[148:151], v[212:213], off offset:128
	global_load_dwordx4 v[152:155], v[212:213], off offset:192
	s_waitcnt vmcnt(8)
	v_pk_fma_f32 v[30:31], v[30:31], v[156:157], v[176:177]
	v_pk_fma_f32 v[32:33], v[32:33], v[158:159], v[178:179]
	v_pk_fma_f32 v[26:27], v[26:27], v[164:165], v[180:181]
	v_pk_fma_f32 v[28:29], v[28:29], v[166:167], v[182:183]
	v_pk_fma_f32 v[22:23], v[22:23], v[168:169], v[184:185]
	v_pk_fma_f32 v[24:25], v[24:25], v[170:171], v[186:187]
	v_pk_fma_f32 v[18:19], v[18:19], v[172:173], v[188:189]
	v_pk_fma_f32 v[20:21], v[20:21], v[174:175], v[190:191]
	global_store_dwordx4 v[214:215], v[30:33], off
	global_store_dwordx4 v[214:215], v[26:29], off offset:64
	global_store_dwordx4 v[214:215], v[22:25], off offset:128
	global_store_dwordx4 v[214:215], v[18:21], off offset:192
	v_lshl_add_u64 v[214:215], v[214:215], 0, v[216:217]
	s_waitcnt vmcnt(4)
	v_pk_fma_f32 v[14:15], v[14:15], v[156:157], v[140:141]
	v_pk_fma_f32 v[16:17], v[16:17], v[158:159], v[142:143]
	v_pk_fma_f32 v[2:3], v[2:3], v[164:165], v[144:145]
	v_pk_fma_f32 v[4:5], v[4:5], v[166:167], v[146:147]
	v_pk_fma_f32 v[6:7], v[6:7], v[168:169], v[148:149]
	v_pk_fma_f32 v[8:9], v[8:9], v[170:171], v[150:151]
	v_pk_fma_f32 v[10:11], v[10:11], v[172:173], v[152:153]
	v_pk_fma_f32 v[12:13], v[12:13], v[174:175], v[154:155]
	global_store_dwordx4 v[214:215], v[14:17], off
	global_store_dwordx4 v[214:215], v[2:5], off offset:64
	global_store_dwordx4 v[214:215], v[6:9], off offset:128
	global_store_dwordx4 v[214:215], v[10:13], off offset:192
	s_add_i32 s7, s7, 1
	s_mul_i32 s0, s7, s39
	s_add_i32 s0, s0, s5
	s_cmpk_gt_i32 s0, 0x7f
	s_cbranch_scc0 .LBB0_961
